# adds P3 merge epilogues with batched gate loads, nt stores and relaxed first waits (peeled first iteration)
# speedup vs baseline: 1.0042x; 1.0042x over previous
.LBB0_548:
	v_ashrrev_i32_e32 v2, 31, v10
	v_lshrrev_b32_e32 v2, 26, v2
	v_add_u32_e32 v2, v10, v2
	v_ashrrev_i32_e32 v11, 6, v2
	v_bfe_i32 v2, v10, 27, 1
	v_lshlrev_b32_e32 v1, 4, v10
	v_lshrrev_b32_e32 v2, 22, v2
	v_add_u32_e32 v2, v1, v2
	v_and_b32_e32 v2, 0xfffffc00, v2
	v_sub_u32_e32 v2, v1, v2
	v_lshrrev_b32_e32 v3, 4, v2
	v_bitop3_b32 v2, v3, v2, 32 bitop3:0x6c
	v_ashrrev_i32_e32 v4, 31, v2
	v_lshrrev_b32_e32 v4, 26, v4
	v_add_u32_e32 v4, v2, v4
	v_lshlrev_b32_e32 v3, 3, v11
	v_ashrrev_i32_e32 v12, 6, v4
	v_and_b32_e32 v4, 0xc0, v4
	v_and_b32_e32 v3, -16, v3
	v_sub_u32_e32 v2, v2, v4
	v_mov_b32_e32 v4, 1
	v_add_u32_e32 v3, v12, v3
	v_ashrrev_i16_sdwa v2, v4, sext(v2) dst_sel:DWORD dst_unused:UNUSED_PAD src0_sel:DWORD src1_sel:BYTE_0
	s_ashr_i32 s0, s7, 3
	v_lshlrev_b32_e32 v5, 5, v11
	v_bfe_i32 v13, v2, 0, 16
	v_lshlrev_b32_e32 v2, 1, v3
	v_lshrrev_b32_e32 v6, 2, v3
	v_and_b32_e32 v7, 3, v12
	s_mov_b32 s7, 0x3fffe0
	v_and_b32_e32 v5, 32, v5
	v_and_b32_e32 v2, 24, v2
	v_and_b32_e32 v6, 4, v6
	v_and_or_b32 v7, v3, s7, v7
	v_or3_b32 v2, v7, v6, v2
	v_add_lshl_u32 v5, v5, v13, 1
	v_add_u32_e32 v1, 0x2000, v1
	v_lshl_add_u32 v132, v2, 10, v5
	v_ashrrev_i32_e32 v2, 31, v1
	v_lshrrev_b32_e32 v2, 22, v2
	s_add_i32 s0, s10, s0
	v_add_u32_e32 v2, v1, v2
	s_ashr_i32 s10, s0, 31
	v_ashrrev_i32_e32 v14, 10, v2
	s_lshr_b32 s10, s10, 27
	v_mul_i32_i24_e32 v2, 0x400, v14
	s_add_i32 s10, s0, s10
	v_sub_u32_e32 v1, v1, v2
	s_ashr_i32 s11, s10, 5
	s_andn2_b32 s10, s10, 31
	v_lshrrev_b32_e32 v2, 4, v1
	s_sub_i32 s10, s0, s10
	v_bitop3_b32 v1, v2, v1, 32 bitop3:0x6c
	s_bfe_i32 s0, s10, 0x80000
	v_lshl_add_u32 v130, v3, 10, v5
	v_ashrrev_i32_e32 v3, 31, v1
	s_bfe_u32 s0, s0, 0x3000c
	v_lshrrev_b32_e32 v3, 26, v3
	s_add_i32 s12, s10, s0
	v_add_u32_e32 v3, v1, v3
	s_bfe_i32 s0, s12, 0x80000
	s_and_b32 s12, s12, 0xf8
	v_lshlrev_b32_e32 v2, 3, v14
	v_ashrrev_i32_e32 v15, 6, v3
	v_and_b32_e32 v3, 0xc0, v3
	s_sub_i32 s10, s10, s12
	v_and_b32_e32 v2, -16, v2
	v_sub_u32_e32 v1, v1, v3
	s_lshl_b32 s11, s11, 3
	s_sext_i32_i16 s0, s0
	s_sext_i32_i8 s10, s10
	s_ashr_i32 s1, s6, 8
	v_add_u32_e32 v2, v15, v2
	v_ashrrev_i16_sdwa v1, v4, sext(v1) dst_sel:DWORD dst_unused:UNUSED_PAD src0_sel:DWORD src1_sel:BYTE_0
	v_and_b32_e32 v4, 3, v15
	s_lshr_b32 s0, s0, 3
	s_add_i32 s64, s11, s10
	v_and_or_b32 v4, v2, s7, v4
	s_ashr_i32 s7, s6, 6
	s_ashr_i32 s65, s64, 31
	s_bfe_i64 s[12:13], s[0:1], 0x100000
	s_lshl_b32 s31, s7, 10
	s_lshl_b64 s[10:11], s[64:65], 18
	s_lshl_b64 s[12:13], s[12:13], 18
	s_add_u32 s70, s42, s12
	v_lshlrev_b32_e32 v5, 5, v14
	v_bfe_i32 v16, v1, 0, 16
	v_lshlrev_b32_e32 v1, 1, v2
	v_lshrrev_b32_e32 v3, 2, v2
	s_addc_u32 s71, s43, s13
	s_add_i32 s65, s31, 0
	v_and_b32_e32 v5, 32, v5
	v_and_b32_e32 v1, 24, v1
	v_and_b32_e32 v3, 4, v3
	s_add_i32 m0, s65, 0x10000
	v_or3_b32 v1, v4, v3, v1
	v_add_lshl_u32 v3, v5, v16, 1
	global_load_lds_dwordx4 v132, s[70:71]
	s_add_i32 m0, s65, 0x12000
	v_lshl_add_u32 v136, v1, 10, v3
	s_add_u32 s12, s70, 0x20000
	global_load_lds_dwordx4 v136, s[70:71]
	s_addc_u32 s13, s71, 0
	s_add_i32 m0, s65, 0x14000
	v_lshl_add_u32 v134, v2, 10, v3
	global_load_lds_dwordx4 v132, s[12:13]
	s_add_i32 m0, s65, 0x16000
	s_add_u32 s66, s74, s10
	s_addc_u32 s67, s75, s11
	s_add_i32 s76, s65, 0x2000
	global_load_lds_dwordx4 v136, s[12:13]
	s_mov_b32 m0, s65
	s_add_u32 s10, s66, 0x20000
	global_load_lds_dwordx4 v130, s[66:67]
	s_mov_b32 m0, s76
	s_addc_u32 s11, s67, 0
	s_add_i32 s77, s65, 0x4000
	global_load_lds_dwordx4 v134, s[66:67]
	s_mov_b32 m0, s77
	s_add_i32 s78, s65, 0x6000
	global_load_lds_dwordx4 v130, s[10:11]
	s_mov_b32 m0, s78
	v_mov_b32_e32 v133, 0
	global_load_lds_dwordx4 v134, s[10:11]
	v_mov_b32_e32 v137, v133
	v_mov_b32_e32 v131, v133
	v_mov_b32_e32 v135, v133
	s_cmp_eq_u32 s1, 1
	s_mov_b32 s100, 0
	s_mov_b32 s79, 0
	v_lshl_add_u64 v[8:9], s[70:71], 0, v[132:133]
	v_lshl_add_u64 v[6:7], s[70:71], 0, v[136:137]
	v_lshl_add_u64 v[2:3], s[66:67], 0, v[130:131]
	s_cselect_b64 s[10:11], -1, 0
	s_cmp_lg_u32 s1, 1
	v_lshl_add_u64 v[4:5], s[66:67], 0, v[134:135]
	s_cbranch_scc1 .LBB0_550
	s_barrier

.LBB0_559:
	s_ashr_i32 s59, s58, 31
	s_lshl_b64 s[6:7], s[58:59], 18
	s_add_u32 s60, s74, s6
	s_addc_u32 s61, s75, s7
	s_and_b64 s[6:7], s[0:1], exec
	s_cselect_b32 s59, s61, s67
	s_cselect_b32 s92, s60, s66
	s_ashr_i32 s57, s56, 31
	s_lshl_b64 s[6:7], s[56:57], 18
	s_add_u32 s62, s42, s6
	s_addc_u32 s63, s43, s7
	s_and_b64 s[6:7], s[0:1], exec
	s_cselect_b32 s57, s63, s71
	s_cselect_b32 s93, s62, s70
	s_add_u32 s66, s66, 0x20080
	s_addc_u32 s67, s67, 0
	s_add_u32 s94, s70, 0x100
	v_mov_b32_e32 v2, 0
	s_addc_u32 s95, s71, 0
	s_mov_b32 s96, -2
	v_mov_b32_e32 v3, v2
	v_mov_b32_e32 v4, v2
	v_mov_b32_e32 v5, v2
	v_mov_b32_e32 v6, v2
	v_mov_b32_e32 v7, v2
	v_mov_b32_e32 v8, v2
	v_mov_b32_e32 v9, v2
	v_mov_b32_e32 v14, v2
	v_mov_b32_e32 v15, v2
	v_mov_b32_e32 v16, v2
	v_mov_b32_e32 v17, v2
	v_mov_b32_e32 v22, v2
	v_mov_b32_e32 v23, v2
	v_mov_b32_e32 v24, v2
	v_mov_b32_e32 v25, v2
	v_mov_b32_e32 v30, v2
	v_mov_b32_e32 v31, v2
	v_mov_b32_e32 v32, v2
	v_mov_b32_e32 v33, v2
	v_mov_b32_e32 v38, v2
	v_mov_b32_e32 v39, v2
	v_mov_b32_e32 v40, v2
	v_mov_b32_e32 v41, v2
	v_mov_b32_e32 v46, v2
	v_mov_b32_e32 v47, v2
	v_mov_b32_e32 v48, v2
	v_mov_b32_e32 v49, v2
	v_mov_b32_e32 v54, v2
	v_mov_b32_e32 v55, v2
	v_mov_b32_e32 v56, v2
	v_mov_b32_e32 v57, v2
	v_mov_b32_e32 v10, v2
	v_mov_b32_e32 v11, v2
	v_mov_b32_e32 v12, v2
	v_mov_b32_e32 v13, v2
	v_mov_b32_e32 v18, v2
	v_mov_b32_e32 v19, v2
	v_mov_b32_e32 v20, v2
	v_mov_b32_e32 v21, v2
	v_mov_b32_e32 v26, v2
	v_mov_b32_e32 v27, v2
	v_mov_b32_e32 v28, v2
	v_mov_b32_e32 v29, v2
	v_mov_b32_e32 v34, v2
	v_mov_b32_e32 v35, v2
	v_mov_b32_e32 v36, v2
	v_mov_b32_e32 v37, v2
	v_mov_b32_e32 v42, v2
	v_mov_b32_e32 v43, v2
	v_mov_b32_e32 v44, v2
	v_mov_b32_e32 v45, v2
	v_mov_b32_e32 v50, v2
	v_mov_b32_e32 v51, v2
	v_mov_b32_e32 v52, v2
	v_mov_b32_e32 v53, v2
	v_mov_b32_e32 v58, v2
	v_mov_b32_e32 v59, v2
	v_mov_b32_e32 v60, v2
	v_mov_b32_e32 v61, v2
	v_mov_b32_e32 v62, v2
	v_mov_b32_e32 v63, v2
	v_mov_b32_e32 v64, v2
	v_mov_b32_e32 v65, v2
	v_mov_b32_e32 v66, v2
	v_mov_b32_e32 v67, v2
	v_mov_b32_e32 v68, v2
	v_mov_b32_e32 v69, v2
	v_mov_b32_e32 v70, v2
	v_mov_b32_e32 v71, v2
	v_mov_b32_e32 v72, v2
	v_mov_b32_e32 v73, v2
	v_mov_b32_e32 v78, v2
	v_mov_b32_e32 v79, v2
	v_mov_b32_e32 v80, v2
	v_mov_b32_e32 v81, v2
	v_mov_b32_e32 v86, v2
	v_mov_b32_e32 v87, v2
	v_mov_b32_e32 v88, v2
	v_mov_b32_e32 v89, v2
	v_mov_b32_e32 v94, v2
	v_mov_b32_e32 v95, v2
	s_cmp_eq_u32 s100, 1
	s_cbranch_scc1 .Lrwp3a_prelaxed
	s_waitcnt vmcnt(0)
.Lrwp3a_pdone:
	v_mov_b32_e32 v96, v2
	v_mov_b32_e32 v97, v2
	v_mov_b32_e32 v102, v2
	v_mov_b32_e32 v103, v2
	v_mov_b32_e32 v104, v2
	v_mov_b32_e32 v105, v2
	v_mov_b32_e32 v110, v2
	v_mov_b32_e32 v111, v2
	v_mov_b32_e32 v112, v2
	v_mov_b32_e32 v113, v2
	v_mov_b32_e32 v118, v2
	v_mov_b32_e32 v119, v2
	v_mov_b32_e32 v120, v2
	v_mov_b32_e32 v121, v2
	v_mov_b32_e32 v74, v2
	v_mov_b32_e32 v75, v2
	v_mov_b32_e32 v76, v2
	v_mov_b32_e32 v77, v2
	v_mov_b32_e32 v82, v2
	v_mov_b32_e32 v83, v2
	v_mov_b32_e32 v84, v2
	v_mov_b32_e32 v85, v2
	v_mov_b32_e32 v90, v2
	v_mov_b32_e32 v91, v2
	v_mov_b32_e32 v92, v2
	v_mov_b32_e32 v93, v2
	v_mov_b32_e32 v98, v2
	v_mov_b32_e32 v99, v2
	v_mov_b32_e32 v100, v2
	v_mov_b32_e32 v101, v2
	v_mov_b32_e32 v106, v2
	v_mov_b32_e32 v107, v2
	v_mov_b32_e32 v108, v2
	v_mov_b32_e32 v109, v2
	v_mov_b32_e32 v114, v2
	v_mov_b32_e32 v115, v2
	v_mov_b32_e32 v116, v2
	v_mov_b32_e32 v117, v2
	v_mov_b32_e32 v122, v2
	v_mov_b32_e32 v123, v2
	v_mov_b32_e32 v124, v2
	v_mov_b32_e32 v125, v2
	v_mov_b32_e32 v126, v2
	v_mov_b32_e32 v127, v2
	v_mov_b32_e32 v128, v2
	v_mov_b32_e32 v129, v2
	s_cmp_lg_u32 s100, 0
	s_cbranch_scc1 .Lrwp3a_first

.Lrwp3a_exit:
	s_and_b64 vcc, exec, s[20:21]
	s_cbranch_vccz .LBB0_563
	s_barrier
.LBB0_563:
	s_lshl_b32 s98, s64, 8
	s_add_i32 s98, s98, s80
	s_lshl_b32 s98, s98, 11
	s_lshl_b32 s99, s91, 8
	s_or_b32 s99, s99, s81
	s_lshl_b32 s99, s99, 1
	s_add_u32 s98, s98, s99
	s_add_u32 s98, s44, s98
	s_addc_u32 s99, s45, 0
	v_lshlrev_b32_e32 v146, 11, v1
	v_lshl_add_u32 v146, v148, 4, v146
	global_load_dwordx4 v[154:157], v146, s[98:99]
	global_load_dwordx4 v[158:161], v146, s[98:99] offset:256
	s_add_u32 s98, s98, 0x8000
	s_addc_u32 s99, s99, 0
	global_load_dwordx4 v[162:165], v146, s[98:99]
	global_load_dwordx4 v[166:169], v146, s[98:99] offset:256
	s_add_u32 s98, s98, 0x8000
	s_addc_u32 s99, s99, 0
	global_load_dwordx4 v[170:173], v146, s[98:99]
	global_load_dwordx4 v[174:177], v146, s[98:99] offset:256
	s_add_u32 s98, s98, 0x8000
	s_addc_u32 s99, s99, 0
	global_load_dwordx4 v[178:181], v146, s[98:99]
	global_load_dwordx4 v[182:185], v146, s[98:99] offset:256
	s_add_u32 s98, s98, 0x28000
	s_addc_u32 s99, s99, 0
	global_load_dwordx4 v[186:189], v146, s[98:99]
	global_load_dwordx4 v[190:193], v146, s[98:99] offset:256
	s_add_u32 s98, s98, 0x8000
	s_addc_u32 s99, s99, 0
	global_load_dwordx4 v[194:197], v146, s[98:99]
	global_load_dwordx4 v[198:201], v146, s[98:99] offset:256
	s_add_u32 s98, s98, 0x8000
	s_addc_u32 s99, s99, 0
	global_load_dwordx4 v[202:205], v146, s[98:99]
	global_load_dwordx4 v[206:209], v146, s[98:99] offset:256
	s_add_u32 s98, s98, 0x8000
	s_addc_u32 s99, s99, 0
	global_load_dwordx4 v[210:213], v146, s[98:99]
	global_load_dwordx4 v[214:217], v146, s[98:99] offset:256
	s_waitcnt vmcnt(15)
	v_lshlrev_b32_e32 v218, 16, v154
	v_and_b32_e32 v154, 0xffff0000, v154
	v_lshlrev_b32_e32 v219, 16, v155
	v_and_b32_e32 v155, 0xffff0000, v155
	v_lshlrev_b32_e32 v220, 16, v156
	v_and_b32_e32 v156, 0xffff0000, v156
	v_lshlrev_b32_e32 v221, 16, v157
	v_and_b32_e32 v157, 0xffff0000, v157
	v_mul_f32_e32 v126, v126, v218
	v_mul_f32_e32 v127, v127, v154
	v_mul_f32_e32 v128, v128, v219
	v_mul_f32_e32 v129, v129, v155
	v_mul_f32_e32 v122, v122, v220
	v_mul_f32_e32 v123, v123, v156
	v_mul_f32_e32 v124, v124, v221
	v_mul_f32_e32 v125, v125, v157
	v_cvt_pk_bf16_f32 v154, v126, v127
	v_cvt_pk_bf16_f32 v155, v128, v129
	v_cvt_pk_bf16_f32 v156, v122, v123
	v_cvt_pk_bf16_f32 v157, v124, v125
	s_sub_u32 s98, s98, 0x58000
	s_subb_u32 s99, s99, 0
	global_store_dwordx4 v146, v[154:157], s[98:99] nt
	s_waitcnt vmcnt(15)
	v_lshlrev_b32_e32 v218, 16, v158
	v_and_b32_e32 v158, 0xffff0000, v158
	v_lshlrev_b32_e32 v219, 16, v159
	v_and_b32_e32 v159, 0xffff0000, v159
	v_lshlrev_b32_e32 v220, 16, v160
	v_and_b32_e32 v160, 0xffff0000, v160
	v_lshlrev_b32_e32 v221, 16, v161
	v_and_b32_e32 v161, 0xffff0000, v161
	v_mul_f32_e32 v118, v118, v218
	v_mul_f32_e32 v119, v119, v158
	v_mul_f32_e32 v120, v120, v219
	v_mul_f32_e32 v121, v121, v159
	v_mul_f32_e32 v110, v110, v220
	v_mul_f32_e32 v111, v111, v160
	v_mul_f32_e32 v112, v112, v221
	v_mul_f32_e32 v113, v113, v161
	v_cvt_pk_bf16_f32 v158, v118, v119
	v_cvt_pk_bf16_f32 v159, v120, v121
	v_cvt_pk_bf16_f32 v160, v110, v111
	v_cvt_pk_bf16_f32 v161, v112, v113
	global_store_dwordx4 v146, v[158:161], s[98:99] offset:256 nt
	s_waitcnt vmcnt(15)
	v_lshlrev_b32_e32 v218, 16, v162
	v_and_b32_e32 v162, 0xffff0000, v162
	v_lshlrev_b32_e32 v219, 16, v163
	v_and_b32_e32 v163, 0xffff0000, v163
	v_lshlrev_b32_e32 v220, 16, v164
	v_and_b32_e32 v164, 0xffff0000, v164
	v_lshlrev_b32_e32 v221, 16, v165
	v_and_b32_e32 v165, 0xffff0000, v165
	v_mul_f32_e32 v114, v114, v218
	v_mul_f32_e32 v115, v115, v162
	v_mul_f32_e32 v116, v116, v219
	v_mul_f32_e32 v117, v117, v163
	v_mul_f32_e32 v106, v106, v220
	v_mul_f32_e32 v107, v107, v164
	v_mul_f32_e32 v108, v108, v221
	v_mul_f32_e32 v109, v109, v165
	v_cvt_pk_bf16_f32 v162, v114, v115
	v_cvt_pk_bf16_f32 v163, v116, v117
	v_cvt_pk_bf16_f32 v164, v106, v107
	v_cvt_pk_bf16_f32 v165, v108, v109
	s_add_u32 s98, s98, 0x8000
	s_addc_u32 s99, s99, 0
	global_store_dwordx4 v146, v[162:165], s[98:99] nt
	s_waitcnt vmcnt(15)
	v_lshlrev_b32_e32 v218, 16, v166
	v_and_b32_e32 v166, 0xffff0000, v166
	v_lshlrev_b32_e32 v219, 16, v167
	v_and_b32_e32 v167, 0xffff0000, v167
	v_lshlrev_b32_e32 v220, 16, v168
	v_and_b32_e32 v168, 0xffff0000, v168
	v_lshlrev_b32_e32 v221, 16, v169
	v_and_b32_e32 v169, 0xffff0000, v169
	v_mul_f32_e32 v102, v102, v218
	v_mul_f32_e32 v103, v103, v166
	v_mul_f32_e32 v104, v104, v219
	v_mul_f32_e32 v105, v105, v167
	v_mul_f32_e32 v94, v94, v220
	v_mul_f32_e32 v95, v95, v168
	v_mul_f32_e32 v96, v96, v221
	v_mul_f32_e32 v97, v97, v169
	v_cvt_pk_bf16_f32 v166, v102, v103
	v_cvt_pk_bf16_f32 v167, v104, v105
	v_cvt_pk_bf16_f32 v168, v94, v95
	v_cvt_pk_bf16_f32 v169, v96, v97
	global_store_dwordx4 v146, v[166:169], s[98:99] offset:256 nt
	s_waitcnt vmcnt(15)
	v_lshlrev_b32_e32 v218, 16, v170
	v_and_b32_e32 v170, 0xffff0000, v170
	v_lshlrev_b32_e32 v219, 16, v171
	v_and_b32_e32 v171, 0xffff0000, v171
	v_lshlrev_b32_e32 v220, 16, v172
	v_and_b32_e32 v172, 0xffff0000, v172
	v_lshlrev_b32_e32 v221, 16, v173
	v_and_b32_e32 v173, 0xffff0000, v173
	v_mul_f32_e32 v98, v98, v218
	v_mul_f32_e32 v99, v99, v170
	v_mul_f32_e32 v100, v100, v219
	v_mul_f32_e32 v101, v101, v171
	v_mul_f32_e32 v90, v90, v220
	v_mul_f32_e32 v91, v91, v172
	v_mul_f32_e32 v92, v92, v221
	v_mul_f32_e32 v93, v93, v173
	v_cvt_pk_bf16_f32 v170, v98, v99
	v_cvt_pk_bf16_f32 v171, v100, v101
	v_cvt_pk_bf16_f32 v172, v90, v91
	v_cvt_pk_bf16_f32 v173, v92, v93
	s_add_u32 s98, s98, 0x8000
	s_addc_u32 s99, s99, 0
	global_store_dwordx4 v146, v[170:173], s[98:99] nt
	s_waitcnt vmcnt(15)
	v_lshlrev_b32_e32 v218, 16, v174
	v_and_b32_e32 v174, 0xffff0000, v174
	v_lshlrev_b32_e32 v219, 16, v175
	v_and_b32_e32 v175, 0xffff0000, v175
	v_lshlrev_b32_e32 v220, 16, v176
	v_and_b32_e32 v176, 0xffff0000, v176
	v_lshlrev_b32_e32 v221, 16, v177
	v_and_b32_e32 v177, 0xffff0000, v177
	v_mul_f32_e32 v86, v86, v218
	v_mul_f32_e32 v87, v87, v174
	v_mul_f32_e32 v88, v88, v219
	v_mul_f32_e32 v89, v89, v175
	v_mul_f32_e32 v78, v78, v220
	v_mul_f32_e32 v79, v79, v176
	v_mul_f32_e32 v80, v80, v221
	v_mul_f32_e32 v81, v81, v177
	v_cvt_pk_bf16_f32 v174, v86, v87
	v_cvt_pk_bf16_f32 v175, v88, v89
	v_cvt_pk_bf16_f32 v176, v78, v79
	v_cvt_pk_bf16_f32 v177, v80, v81
	global_store_dwordx4 v146, v[174:177], s[98:99] offset:256 nt
	s_waitcnt vmcnt(15)
	v_lshlrev_b32_e32 v218, 16, v178
	v_and_b32_e32 v178, 0xffff0000, v178
	v_lshlrev_b32_e32 v219, 16, v179
	v_and_b32_e32 v179, 0xffff0000, v179
	v_lshlrev_b32_e32 v220, 16, v180
	v_and_b32_e32 v180, 0xffff0000, v180
	v_lshlrev_b32_e32 v221, 16, v181
	v_and_b32_e32 v181, 0xffff0000, v181
	v_mul_f32_e32 v82, v82, v218
	v_mul_f32_e32 v83, v83, v178
	v_mul_f32_e32 v84, v84, v219
	v_mul_f32_e32 v85, v85, v179
	v_mul_f32_e32 v74, v74, v220
	v_mul_f32_e32 v75, v75, v180
	v_mul_f32_e32 v76, v76, v221
	v_mul_f32_e32 v77, v77, v181
	v_cvt_pk_bf16_f32 v178, v82, v83
	v_cvt_pk_bf16_f32 v179, v84, v85
	v_cvt_pk_bf16_f32 v180, v74, v75
	v_cvt_pk_bf16_f32 v181, v76, v77
	s_add_u32 s98, s98, 0x8000
	s_addc_u32 s99, s99, 0
	global_store_dwordx4 v146, v[178:181], s[98:99] nt
	s_waitcnt vmcnt(15)
	v_lshlrev_b32_e32 v218, 16, v182
	v_and_b32_e32 v182, 0xffff0000, v182
	v_lshlrev_b32_e32 v219, 16, v183
	v_and_b32_e32 v183, 0xffff0000, v183
	v_lshlrev_b32_e32 v220, 16, v184
	v_and_b32_e32 v184, 0xffff0000, v184
	v_lshlrev_b32_e32 v221, 16, v185
	v_and_b32_e32 v185, 0xffff0000, v185
	v_mul_f32_e32 v70, v70, v218
	v_mul_f32_e32 v71, v71, v182
	v_mul_f32_e32 v72, v72, v219
	v_mul_f32_e32 v73, v73, v183
	v_mul_f32_e32 v66, v66, v220
	v_mul_f32_e32 v67, v67, v184
	v_mul_f32_e32 v68, v68, v221
	v_mul_f32_e32 v69, v69, v185
	v_cvt_pk_bf16_f32 v182, v70, v71
	v_cvt_pk_bf16_f32 v183, v72, v73
	v_cvt_pk_bf16_f32 v184, v66, v67
	v_cvt_pk_bf16_f32 v185, v68, v69
	global_store_dwordx4 v146, v[182:185], s[98:99] offset:256 nt
	s_waitcnt vmcnt(15)
	v_lshlrev_b32_e32 v218, 16, v186
	v_and_b32_e32 v186, 0xffff0000, v186
	v_lshlrev_b32_e32 v219, 16, v187
	v_and_b32_e32 v187, 0xffff0000, v187
	v_lshlrev_b32_e32 v220, 16, v188
	v_and_b32_e32 v188, 0xffff0000, v188
	v_lshlrev_b32_e32 v221, 16, v189
	v_and_b32_e32 v189, 0xffff0000, v189
	v_mul_f32_e32 v62, v62, v218
	v_mul_f32_e32 v63, v63, v186
	v_mul_f32_e32 v64, v64, v219
	v_mul_f32_e32 v65, v65, v187
	v_mul_f32_e32 v58, v58, v220
	v_mul_f32_e32 v59, v59, v188
	v_mul_f32_e32 v60, v60, v221
	v_mul_f32_e32 v61, v61, v189
	v_cvt_pk_bf16_f32 v186, v62, v63
	v_cvt_pk_bf16_f32 v187, v64, v65
	v_cvt_pk_bf16_f32 v188, v58, v59
	v_cvt_pk_bf16_f32 v189, v60, v61
	s_add_u32 s98, s98, 0x28000
	s_addc_u32 s99, s99, 0
	global_store_dwordx4 v146, v[186:189], s[98:99] nt
	s_waitcnt vmcnt(15)
	v_lshlrev_b32_e32 v218, 16, v190
	v_and_b32_e32 v190, 0xffff0000, v190
	v_lshlrev_b32_e32 v219, 16, v191
	v_and_b32_e32 v191, 0xffff0000, v191
	v_lshlrev_b32_e32 v220, 16, v192
	v_and_b32_e32 v192, 0xffff0000, v192
	v_lshlrev_b32_e32 v221, 16, v193
	v_and_b32_e32 v193, 0xffff0000, v193
	v_mul_f32_e32 v54, v54, v218
	v_mul_f32_e32 v55, v55, v190
	v_mul_f32_e32 v56, v56, v219
	v_mul_f32_e32 v57, v57, v191
	v_mul_f32_e32 v46, v46, v220
	v_mul_f32_e32 v47, v47, v192
	v_mul_f32_e32 v48, v48, v221
	v_mul_f32_e32 v49, v49, v193
	v_cvt_pk_bf16_f32 v190, v54, v55
	v_cvt_pk_bf16_f32 v191, v56, v57
	v_cvt_pk_bf16_f32 v192, v46, v47
	v_cvt_pk_bf16_f32 v193, v48, v49
	global_store_dwordx4 v146, v[190:193], s[98:99] offset:256 nt
	s_waitcnt vmcnt(15)
	v_lshlrev_b32_e32 v218, 16, v194
	v_and_b32_e32 v194, 0xffff0000, v194
	v_lshlrev_b32_e32 v219, 16, v195
	v_and_b32_e32 v195, 0xffff0000, v195
	v_lshlrev_b32_e32 v220, 16, v196
	v_and_b32_e32 v196, 0xffff0000, v196
	v_lshlrev_b32_e32 v221, 16, v197
	v_and_b32_e32 v197, 0xffff0000, v197
	v_mul_f32_e32 v50, v50, v218
	v_mul_f32_e32 v51, v51, v194
	v_mul_f32_e32 v52, v52, v219
	v_mul_f32_e32 v53, v53, v195
	v_mul_f32_e32 v42, v42, v220
	v_mul_f32_e32 v43, v43, v196
	v_mul_f32_e32 v44, v44, v221
	v_mul_f32_e32 v45, v45, v197
	v_cvt_pk_bf16_f32 v194, v50, v51
	v_cvt_pk_bf16_f32 v195, v52, v53
	v_cvt_pk_bf16_f32 v196, v42, v43
	v_cvt_pk_bf16_f32 v197, v44, v45
	s_add_u32 s98, s98, 0x8000
	s_addc_u32 s99, s99, 0
	global_store_dwordx4 v146, v[194:197], s[98:99] nt
	s_waitcnt vmcnt(15)
	v_lshlrev_b32_e32 v218, 16, v198
	v_and_b32_e32 v198, 0xffff0000, v198
	v_lshlrev_b32_e32 v219, 16, v199
	v_and_b32_e32 v199, 0xffff0000, v199
	v_lshlrev_b32_e32 v220, 16, v200
	v_and_b32_e32 v200, 0xffff0000, v200
	v_lshlrev_b32_e32 v221, 16, v201
	v_and_b32_e32 v201, 0xffff0000, v201
	v_mul_f32_e32 v38, v38, v218
	v_mul_f32_e32 v39, v39, v198
	v_mul_f32_e32 v40, v40, v219
	v_mul_f32_e32 v41, v41, v199
	v_mul_f32_e32 v30, v30, v220
	v_mul_f32_e32 v31, v31, v200
	v_mul_f32_e32 v32, v32, v221
	v_mul_f32_e32 v33, v33, v201
	v_cvt_pk_bf16_f32 v198, v38, v39
	v_cvt_pk_bf16_f32 v199, v40, v41
	v_cvt_pk_bf16_f32 v200, v30, v31
	v_cvt_pk_bf16_f32 v201, v32, v33
	global_store_dwordx4 v146, v[198:201], s[98:99] offset:256 nt
	s_waitcnt vmcnt(15)
	v_lshlrev_b32_e32 v218, 16, v202
	v_and_b32_e32 v202, 0xffff0000, v202
	v_lshlrev_b32_e32 v219, 16, v203
	v_and_b32_e32 v203, 0xffff0000, v203
	v_lshlrev_b32_e32 v220, 16, v204
	v_and_b32_e32 v204, 0xffff0000, v204
	v_lshlrev_b32_e32 v221, 16, v205
	v_and_b32_e32 v205, 0xffff0000, v205
	v_mul_f32_e32 v34, v34, v218
	v_mul_f32_e32 v35, v35, v202
	v_mul_f32_e32 v36, v36, v219
	v_mul_f32_e32 v37, v37, v203
	v_mul_f32_e32 v26, v26, v220
	v_mul_f32_e32 v27, v27, v204
	v_mul_f32_e32 v28, v28, v221
	v_mul_f32_e32 v29, v29, v205
	v_cvt_pk_bf16_f32 v202, v34, v35
	v_cvt_pk_bf16_f32 v203, v36, v37
	v_cvt_pk_bf16_f32 v204, v26, v27
	v_cvt_pk_bf16_f32 v205, v28, v29
	s_add_u32 s98, s98, 0x8000
	s_addc_u32 s99, s99, 0
	global_store_dwordx4 v146, v[202:205], s[98:99] nt
	s_waitcnt vmcnt(15)
	v_lshlrev_b32_e32 v218, 16, v206
	v_and_b32_e32 v206, 0xffff0000, v206
	v_lshlrev_b32_e32 v219, 16, v207
	v_and_b32_e32 v207, 0xffff0000, v207
	v_lshlrev_b32_e32 v220, 16, v208
	v_and_b32_e32 v208, 0xffff0000, v208
	v_lshlrev_b32_e32 v221, 16, v209
	v_and_b32_e32 v209, 0xffff0000, v209
	v_mul_f32_e32 v22, v22, v218
	v_mul_f32_e32 v23, v23, v206
	v_mul_f32_e32 v24, v24, v219
	v_mul_f32_e32 v25, v25, v207
	v_mul_f32_e32 v14, v14, v220
	v_mul_f32_e32 v15, v15, v208
	v_mul_f32_e32 v16, v16, v221
	v_mul_f32_e32 v17, v17, v209
	v_cvt_pk_bf16_f32 v206, v22, v23
	v_cvt_pk_bf16_f32 v207, v24, v25
	v_cvt_pk_bf16_f32 v208, v14, v15
	v_cvt_pk_bf16_f32 v209, v16, v17
	global_store_dwordx4 v146, v[206:209], s[98:99] offset:256 nt
	s_waitcnt vmcnt(15)
	v_lshlrev_b32_e32 v218, 16, v210
	v_and_b32_e32 v210, 0xffff0000, v210
	v_lshlrev_b32_e32 v219, 16, v211
	v_and_b32_e32 v211, 0xffff0000, v211
	v_lshlrev_b32_e32 v220, 16, v212
	v_and_b32_e32 v212, 0xffff0000, v212
	v_lshlrev_b32_e32 v221, 16, v213
	v_and_b32_e32 v213, 0xffff0000, v213
	v_mul_f32_e32 v18, v18, v218
	v_mul_f32_e32 v19, v19, v210
	v_mul_f32_e32 v20, v20, v219
	v_mul_f32_e32 v21, v21, v211
	v_mul_f32_e32 v10, v10, v220
	v_mul_f32_e32 v11, v11, v212
	v_mul_f32_e32 v12, v12, v221
	v_mul_f32_e32 v13, v13, v213
	v_cvt_pk_bf16_f32 v210, v18, v19
	v_cvt_pk_bf16_f32 v211, v20, v21
	v_cvt_pk_bf16_f32 v212, v10, v11
	v_cvt_pk_bf16_f32 v213, v12, v13
	s_add_u32 s98, s98, 0x8000
	s_addc_u32 s99, s99, 0
	global_store_dwordx4 v146, v[210:213], s[98:99] nt
	s_waitcnt vmcnt(15)
	v_lshlrev_b32_e32 v218, 16, v214
	v_and_b32_e32 v214, 0xffff0000, v214
	v_lshlrev_b32_e32 v219, 16, v215
	v_and_b32_e32 v215, 0xffff0000, v215
	v_lshlrev_b32_e32 v220, 16, v216
	v_and_b32_e32 v216, 0xffff0000, v216
	v_lshlrev_b32_e32 v221, 16, v217
	v_and_b32_e32 v217, 0xffff0000, v217
	v_mul_f32_e32 v6, v6, v218
	v_mul_f32_e32 v7, v7, v214
	v_mul_f32_e32 v8, v8, v219
	v_mul_f32_e32 v9, v9, v215
	v_mul_f32_e32 v2, v2, v220
	v_mul_f32_e32 v3, v3, v216
	v_mul_f32_e32 v4, v4, v221
	v_mul_f32_e32 v5, v5, v217
	v_cvt_pk_bf16_f32 v214, v6, v7
	v_cvt_pk_bf16_f32 v215, v8, v9
	v_cvt_pk_bf16_f32 v216, v2, v3
	v_cvt_pk_bf16_f32 v217, v4, v5
	global_store_dwordx4 v146, v[214:217], s[98:99] offset:256 nt
	s_andn2_b64 vcc, exec, s[0:1]
	s_mov_b64 s[0:1], -1
	s_mov_b32 s100, 1
	s_cbranch_vccnz .LBB0_552
	s_andn2_b64 vcc, exec, s[10:11]
	s_cbranch_vccnz .LBB0_551
	s_barrier
	s_branch .LBB0_551
.Lrwp3a_first:
	ds_read_b128 v[154:157], v150
	ds_read_b128 v[158:161], v150 offset:1024
	ds_read_b128 v[162:165], v150 offset:2048
	ds_read_b128 v[166:169], v150 offset:3072
	ds_read_b128 v[170:173], v151
	ds_read_b128 v[174:177], v151 offset:1024
	ds_read_b128 v[178:181], v151 offset:2048
	ds_read_b128 v[182:185], v151 offset:3072
	s_add_u32 s6, s66, 0xfffe0080
	s_addc_u32 s7, s67, -1
	s_cmp_eq_u32 s96, 4
	s_cselect_b32 s73, s59, s7
	s_cselect_b32 s72, s92, s6
	s_cselect_b32 s71, s57, s95
	s_cselect_b32 s70, s93, s94
	v_lshl_add_u64 v[146:147], s[66:67], 0, v[138:139]
	s_add_i32 m0, s65, 0xc000
	ds_read_b128 v[186:189], v152
	ds_read_b128 v[190:193], v152 offset:1024
	ds_read_b128 v[194:197], v152 offset:2048
	ds_read_b128 v[198:201], v152 offset:3072
	ds_read_b128 v[202:205], v152 offset:4096
	ds_read_b128 v[206:209], v152 offset:5120
	ds_read_b128 v[210:213], v152 offset:6144
	ds_read_b128 v[214:217], v152 offset:7168
	global_load_lds_dwordx4 v[146:147], off
	v_lshl_add_u64 v[146:147], s[66:67], 0, v[140:141]
	s_add_i32 m0, s65, 0xe000
	s_nop 0
	global_load_lds_dwordx4 v[146:147], off
	s_cmp_eq_u32 s100, 1
	s_cbranch_scc1 .Lrwp3a_a16
	s_waitcnt vmcnt(8)
	s_branch .Lrwp3a_adone

.Lrwp3a_adone:
	s_waitcnt lgkmcnt(0)
	s_barrier
	s_setprio 1
	s_waitcnt lgkmcnt(0)
	v_mfma_f32_16x16x32_bf16 v[126:129], v[154:157], v[186:189], v[126:129]
	v_mfma_f32_16x16x32_bf16 v[122:125], v[162:165], v[186:189], v[122:125]
	v_mfma_f32_16x16x32_bf16 v[114:117], v[154:157], v[194:197], v[114:117]
	v_mfma_f32_16x16x32_bf16 v[106:109], v[162:165], v[194:197], v[106:109]
	v_mfma_f32_16x16x32_bf16 v[98:101], v[154:157], v[202:205], v[98:101]
	v_mfma_f32_16x16x32_bf16 v[90:93], v[162:165], v[202:205], v[90:93]
	v_mfma_f32_16x16x32_bf16 v[82:85], v[154:157], v[210:213], v[82:85]
	v_mfma_f32_16x16x32_bf16 v[74:77], v[162:165], v[210:213], v[74:77]
	v_mfma_f32_16x16x32_bf16 v[126:129], v[158:161], v[190:193], v[126:129]
	v_mfma_f32_16x16x32_bf16 v[122:125], v[166:169], v[190:193], v[122:125]
	v_mfma_f32_16x16x32_bf16 v[114:117], v[158:161], v[198:201], v[114:117]
	v_mfma_f32_16x16x32_bf16 v[106:109], v[166:169], v[198:201], v[106:109]
	v_mfma_f32_16x16x32_bf16 v[98:101], v[158:161], v[206:209], v[98:101]
	v_mfma_f32_16x16x32_bf16 v[90:93], v[166:169], v[206:209], v[90:93]
	v_mfma_f32_16x16x32_bf16 v[82:85], v[158:161], v[214:217], v[82:85]
	v_mfma_f32_16x16x32_bf16 v[74:77], v[166:169], v[214:217], v[74:77]
	s_setprio 0
	s_setprio 1
	v_mfma_f32_16x16x32_bf16 v[118:121], v[170:173], v[186:189], v[118:121]
	v_mfma_f32_16x16x32_bf16 v[110:113], v[178:181], v[186:189], v[110:113]
	v_mfma_f32_16x16x32_bf16 v[102:105], v[170:173], v[194:197], v[102:105]
	v_mfma_f32_16x16x32_bf16 v[94:97], v[178:181], v[194:197], v[94:97]
	v_mfma_f32_16x16x32_bf16 v[86:89], v[170:173], v[202:205], v[86:89]
	v_mfma_f32_16x16x32_bf16 v[78:81], v[178:181], v[202:205], v[78:81]
	v_mfma_f32_16x16x32_bf16 v[70:73], v[170:173], v[210:213], v[70:73]
	v_mfma_f32_16x16x32_bf16 v[66:69], v[178:181], v[210:213], v[66:69]
	v_mfma_f32_16x16x32_bf16 v[118:121], v[174:177], v[190:193], v[118:121]
	v_mfma_f32_16x16x32_bf16 v[110:113], v[182:185], v[190:193], v[110:113]
	v_mfma_f32_16x16x32_bf16 v[102:105], v[174:177], v[198:201], v[102:105]
	v_mfma_f32_16x16x32_bf16 v[94:97], v[182:185], v[198:201], v[94:97]
	v_mfma_f32_16x16x32_bf16 v[86:89], v[174:177], v[206:209], v[86:89]
	v_mfma_f32_16x16x32_bf16 v[78:81], v[182:185], v[206:209], v[78:81]
	v_mfma_f32_16x16x32_bf16 v[70:73], v[174:177], v[214:217], v[70:73]
	v_mfma_f32_16x16x32_bf16 v[66:69], v[182:185], v[214:217], v[66:69]
	s_setprio 0
	s_barrier
	s_add_i32 s6, s85, s31
	v_lshl_add_u64 v[146:147], s[70:71], 0, v[132:133]
	s_mov_b32 m0, s6
	ds_read_b128 v[186:189], v152 offset:16384
	ds_read_b128 v[190:193], v152 offset:17408
	ds_read_b128 v[194:197], v152 offset:18432
	ds_read_b128 v[198:201], v152 offset:19456
	ds_read_b128 v[202:205], v152 offset:20480
	ds_read_b128 v[206:209], v152 offset:21504
	ds_read_b128 v[210:213], v152 offset:22528
	ds_read_b128 v[214:217], v152 offset:23552
	global_load_lds_dwordx4 v[146:147], off
	s_add_i32 m0, s6, 0x2000
	s_add_u32 s6, s70, 0x20000
	v_lshl_add_u64 v[218:219], s[70:71], 0, v[136:137]
	s_addc_u32 s7, s71, 0
	s_add_i32 s97, s86, s31
	global_load_lds_dwordx4 v[218:219], off
	v_lshl_add_u64 v[220:221], s[6:7], 0, v[132:133]
	s_mov_b32 m0, s97
	v_lshl_add_u64 v[222:223], s[72:73], 0, v[134:135]
	global_load_lds_dwordx4 v[220:221], off
	v_lshl_add_u64 v[220:221], s[6:7], 0, v[136:137]
	s_add_i32 m0, s97, 0x2000
	s_nop 0
	global_load_lds_dwordx4 v[220:221], off
	v_lshl_add_u64 v[220:221], s[72:73], 0, v[130:131]
	s_mov_b32 m0, s65
	s_nop 0
	global_load_lds_dwordx4 v[220:221], off
	s_mov_b32 m0, s76
	s_nop 0
	global_load_lds_dwordx4 v[222:223], off
	s_cmp_eq_u32 s100, 1
	s_cbranch_scc1 .Lrwp3a_b16
	s_waitcnt vmcnt(8)
	s_branch .Lrwp3a_bdone

.Lrwp3a_bdone:
	s_mov_b32 s100, 0
	s_waitcnt lgkmcnt(0)
	s_barrier
	s_setprio 1
	s_waitcnt lgkmcnt(0)
	v_mfma_f32_16x16x32_bf16 v[62:65], v[154:157], v[186:189], v[62:65]
	v_mfma_f32_16x16x32_bf16 v[58:61], v[162:165], v[186:189], v[58:61]
	v_mfma_f32_16x16x32_bf16 v[50:53], v[154:157], v[194:197], v[50:53]
	v_mfma_f32_16x16x32_bf16 v[42:45], v[162:165], v[194:197], v[42:45]
	v_mfma_f32_16x16x32_bf16 v[34:37], v[154:157], v[202:205], v[34:37]
	v_mfma_f32_16x16x32_bf16 v[26:29], v[162:165], v[202:205], v[26:29]
	v_mfma_f32_16x16x32_bf16 v[18:21], v[154:157], v[210:213], v[18:21]
	v_mfma_f32_16x16x32_bf16 v[10:13], v[162:165], v[210:213], v[10:13]
	v_mfma_f32_16x16x32_bf16 v[62:65], v[158:161], v[190:193], v[62:65]
	v_mfma_f32_16x16x32_bf16 v[58:61], v[166:169], v[190:193], v[58:61]
	v_mfma_f32_16x16x32_bf16 v[50:53], v[158:161], v[198:201], v[50:53]
	v_mfma_f32_16x16x32_bf16 v[42:45], v[166:169], v[198:201], v[42:45]
	v_mfma_f32_16x16x32_bf16 v[34:37], v[158:161], v[206:209], v[34:37]
	v_mfma_f32_16x16x32_bf16 v[26:29], v[166:169], v[206:209], v[26:29]
	v_mfma_f32_16x16x32_bf16 v[18:21], v[158:161], v[214:217], v[18:21]
	v_mfma_f32_16x16x32_bf16 v[10:13], v[166:169], v[214:217], v[10:13]
	s_setprio 0
	s_setprio 1
	v_mfma_f32_16x16x32_bf16 v[54:57], v[170:173], v[186:189], v[54:57]
	v_mfma_f32_16x16x32_bf16 v[46:49], v[178:181], v[186:189], v[46:49]
	v_mfma_f32_16x16x32_bf16 v[38:41], v[170:173], v[194:197], v[38:41]
	v_mfma_f32_16x16x32_bf16 v[30:33], v[178:181], v[194:197], v[30:33]
	v_mfma_f32_16x16x32_bf16 v[22:25], v[170:173], v[202:205], v[22:25]
	v_mfma_f32_16x16x32_bf16 v[14:17], v[178:181], v[202:205], v[14:17]
	v_mfma_f32_16x16x32_bf16 v[6:9], v[170:173], v[210:213], v[6:9]
	v_mfma_f32_16x16x32_bf16 v[2:5], v[178:181], v[210:213], v[2:5]
	v_mfma_f32_16x16x32_bf16 v[54:57], v[174:177], v[190:193], v[54:57]
	v_mfma_f32_16x16x32_bf16 v[46:49], v[182:185], v[190:193], v[46:49]
	v_mfma_f32_16x16x32_bf16 v[38:41], v[174:177], v[198:201], v[38:41]
	v_mfma_f32_16x16x32_bf16 v[30:33], v[182:185], v[198:201], v[30:33]
	v_mfma_f32_16x16x32_bf16 v[22:25], v[174:177], v[206:209], v[22:25]
	v_mfma_f32_16x16x32_bf16 v[14:17], v[182:185], v[206:209], v[14:17]
	v_mfma_f32_16x16x32_bf16 v[6:9], v[174:177], v[214:217], v[6:9]
	v_mfma_f32_16x16x32_bf16 v[2:5], v[182:185], v[214:217], v[2:5]
	s_setprio 0
	s_barrier
	s_add_i32 s97, 0, 0x18000
	v_add_u32_e32 v153, s97, v149
	s_add_i32 vcc_lo, 0, 0x1c000
	ds_read_b128 v[154:157], v153
	ds_read_b128 v[158:161], v153 offset:1024
	ds_read_b128 v[162:165], v153 offset:2048
	ds_read_b128 v[166:169], v153 offset:3072
	v_add_u32_e32 v153, vcc_lo, v149
	ds_read_b128 v[170:173], v153
	ds_read_b128 v[174:177], v153 offset:1024
	ds_read_b128 v[178:181], v153 offset:2048
	ds_read_b128 v[182:185], v153 offset:3072
	s_add_u32 s6, s72, 0x20000
	s_addc_u32 s7, s73, 0
	s_mov_b32 m0, s77
	v_lshl_add_u64 v[224:225], s[6:7], 0, v[130:131]
	ds_read_b128 v[186:189], v152 offset:32768
	ds_read_b128 v[190:193], v152 offset:33792
	ds_read_b128 v[194:197], v152 offset:34816
	ds_read_b128 v[198:201], v152 offset:35840
	ds_read_b128 v[202:205], v152 offset:36864
	ds_read_b128 v[206:209], v152 offset:37888
	ds_read_b128 v[210:213], v152 offset:38912
	ds_read_b128 v[214:217], v152 offset:39936
	global_load_lds_dwordx4 v[224:225], off
	v_lshl_add_u64 v[224:225], s[6:7], 0, v[134:135]
	s_mov_b32 m0, s78
	s_nop 0
	global_load_lds_dwordx4 v[224:225], off
	s_waitcnt vmcnt(8)
	s_waitcnt lgkmcnt(0)
	s_barrier
	s_setprio 1
	s_waitcnt lgkmcnt(0)
	v_mfma_f32_16x16x32_bf16 v[126:129], v[154:157], v[186:189], v[126:129]
	v_mfma_f32_16x16x32_bf16 v[122:125], v[162:165], v[186:189], v[122:125]
	v_mfma_f32_16x16x32_bf16 v[114:117], v[154:157], v[194:197], v[114:117]
	v_mfma_f32_16x16x32_bf16 v[106:109], v[162:165], v[194:197], v[106:109]
	v_mfma_f32_16x16x32_bf16 v[98:101], v[154:157], v[202:205], v[98:101]
	v_mfma_f32_16x16x32_bf16 v[90:93], v[162:165], v[202:205], v[90:93]
	v_mfma_f32_16x16x32_bf16 v[82:85], v[154:157], v[210:213], v[82:85]
	v_mfma_f32_16x16x32_bf16 v[74:77], v[162:165], v[210:213], v[74:77]
	v_mfma_f32_16x16x32_bf16 v[126:129], v[158:161], v[190:193], v[126:129]
	v_mfma_f32_16x16x32_bf16 v[122:125], v[166:169], v[190:193], v[122:125]
	v_mfma_f32_16x16x32_bf16 v[114:117], v[158:161], v[198:201], v[114:117]
	v_mfma_f32_16x16x32_bf16 v[106:109], v[166:169], v[198:201], v[106:109]
	v_mfma_f32_16x16x32_bf16 v[98:101], v[158:161], v[206:209], v[98:101]
	v_mfma_f32_16x16x32_bf16 v[90:93], v[166:169], v[206:209], v[90:93]
	v_mfma_f32_16x16x32_bf16 v[82:85], v[158:161], v[214:217], v[82:85]
	v_mfma_f32_16x16x32_bf16 v[74:77], v[166:169], v[214:217], v[74:77]
	s_setprio 0
	s_setprio 1
	v_mfma_f32_16x16x32_bf16 v[118:121], v[170:173], v[186:189], v[118:121]
	v_mfma_f32_16x16x32_bf16 v[110:113], v[178:181], v[186:189], v[110:113]
	v_mfma_f32_16x16x32_bf16 v[102:105], v[170:173], v[194:197], v[102:105]
	v_mfma_f32_16x16x32_bf16 v[94:97], v[178:181], v[194:197], v[94:97]
	v_mfma_f32_16x16x32_bf16 v[86:89], v[170:173], v[202:205], v[86:89]
	v_mfma_f32_16x16x32_bf16 v[78:81], v[178:181], v[202:205], v[78:81]
	v_mfma_f32_16x16x32_bf16 v[70:73], v[170:173], v[210:213], v[70:73]
	v_mfma_f32_16x16x32_bf16 v[66:69], v[178:181], v[210:213], v[66:69]
	v_mfma_f32_16x16x32_bf16 v[118:121], v[174:177], v[190:193], v[118:121]
	v_mfma_f32_16x16x32_bf16 v[110:113], v[182:185], v[190:193], v[110:113]
	v_mfma_f32_16x16x32_bf16 v[102:105], v[174:177], v[198:201], v[102:105]
	v_mfma_f32_16x16x32_bf16 v[94:97], v[182:185], v[198:201], v[94:97]
	v_mfma_f32_16x16x32_bf16 v[86:89], v[174:177], v[206:209], v[86:89]
	v_mfma_f32_16x16x32_bf16 v[78:81], v[182:185], v[206:209], v[78:81]
	v_mfma_f32_16x16x32_bf16 v[70:73], v[174:177], v[214:217], v[70:73]
	v_mfma_f32_16x16x32_bf16 v[66:69], v[182:185], v[214:217], v[66:69]
	s_setprio 0
	s_barrier
	s_add_i32 s6, s97, s31
	v_lshl_add_u64 v[146:147], v[146:147], 0, s[12:13]
	s_mov_b32 m0, s6
	ds_read_b128 v[186:189], v152 offset:49152
	ds_read_b128 v[190:193], v152 offset:50176
	ds_read_b128 v[194:197], v152 offset:51200
	ds_read_b128 v[198:201], v152 offset:52224
	ds_read_b128 v[202:205], v152 offset:53248
	ds_read_b128 v[206:209], v152 offset:54272
	ds_read_b128 v[210:213], v152 offset:55296
	ds_read_b128 v[214:217], v152 offset:56320
	global_load_lds_dwordx4 v[146:147], off
	s_add_i32 m0, s6, 0x2000
	s_add_u32 s6, s70, 0x20080
	v_lshl_add_u64 v[146:147], v[218:219], 0, s[12:13]
	s_addc_u32 s7, s71, 0
	s_add_i32 s70, vcc_lo, s31
	global_load_lds_dwordx4 v[146:147], off
	v_lshl_add_u64 v[146:147], s[6:7], 0, v[132:133]
	s_mov_b32 m0, s70
	s_nop 0
	global_load_lds_dwordx4 v[146:147], off
	v_lshl_add_u64 v[146:147], s[6:7], 0, v[136:137]
	s_add_i32 m0, s70, 0x2000
	s_nop 0
	global_load_lds_dwordx4 v[146:147], off
	v_lshl_add_u64 v[146:147], v[220:221], 0, s[12:13]
	s_mov_b32 m0, s82
	s_nop 0
	global_load_lds_dwordx4 v[146:147], off
	v_lshl_add_u64 v[146:147], v[222:223], 0, s[12:13]
	s_mov_b32 m0, s83
	s_nop 0
	global_load_lds_dwordx4 v[146:147], off
	s_waitcnt vmcnt(8)
	s_waitcnt lgkmcnt(0)
	s_barrier
	s_setprio 1
	s_waitcnt lgkmcnt(0)
	v_mfma_f32_16x16x32_bf16 v[62:65], v[154:157], v[186:189], v[62:65]
	v_mfma_f32_16x16x32_bf16 v[58:61], v[162:165], v[186:189], v[58:61]
	v_mfma_f32_16x16x32_bf16 v[50:53], v[154:157], v[194:197], v[50:53]
	v_mfma_f32_16x16x32_bf16 v[42:45], v[162:165], v[194:197], v[42:45]
	v_mfma_f32_16x16x32_bf16 v[34:37], v[154:157], v[202:205], v[34:37]
	v_mfma_f32_16x16x32_bf16 v[26:29], v[162:165], v[202:205], v[26:29]
	v_mfma_f32_16x16x32_bf16 v[18:21], v[154:157], v[210:213], v[18:21]
	v_mfma_f32_16x16x32_bf16 v[10:13], v[162:165], v[210:213], v[10:13]
	v_mfma_f32_16x16x32_bf16 v[62:65], v[158:161], v[190:193], v[62:65]
	v_mfma_f32_16x16x32_bf16 v[58:61], v[166:169], v[190:193], v[58:61]
	v_mfma_f32_16x16x32_bf16 v[50:53], v[158:161], v[198:201], v[50:53]
	v_mfma_f32_16x16x32_bf16 v[42:45], v[166:169], v[198:201], v[42:45]
	v_mfma_f32_16x16x32_bf16 v[34:37], v[158:161], v[206:209], v[34:37]
	v_mfma_f32_16x16x32_bf16 v[26:29], v[166:169], v[206:209], v[26:29]
	v_mfma_f32_16x16x32_bf16 v[18:21], v[158:161], v[214:217], v[18:21]
	v_mfma_f32_16x16x32_bf16 v[10:13], v[166:169], v[214:217], v[10:13]
	s_setprio 0
	s_setprio 1
	v_mfma_f32_16x16x32_bf16 v[54:57], v[170:173], v[186:189], v[54:57]
	v_mfma_f32_16x16x32_bf16 v[46:49], v[178:181], v[186:189], v[46:49]
	v_mfma_f32_16x16x32_bf16 v[38:41], v[170:173], v[194:197], v[38:41]
	v_mfma_f32_16x16x32_bf16 v[30:33], v[178:181], v[194:197], v[30:33]
	v_mfma_f32_16x16x32_bf16 v[22:25], v[170:173], v[202:205], v[22:25]
	v_mfma_f32_16x16x32_bf16 v[14:17], v[178:181], v[202:205], v[14:17]
	v_mfma_f32_16x16x32_bf16 v[6:9], v[170:173], v[210:213], v[6:9]
	v_mfma_f32_16x16x32_bf16 v[2:5], v[178:181], v[210:213], v[2:5]
	v_mfma_f32_16x16x32_bf16 v[54:57], v[174:177], v[190:193], v[54:57]
	v_mfma_f32_16x16x32_bf16 v[46:49], v[182:185], v[190:193], v[46:49]
	v_mfma_f32_16x16x32_bf16 v[38:41], v[174:177], v[198:201], v[38:41]
	v_mfma_f32_16x16x32_bf16 v[30:33], v[182:185], v[198:201], v[30:33]
	v_mfma_f32_16x16x32_bf16 v[22:25], v[174:177], v[206:209], v[22:25]
	v_mfma_f32_16x16x32_bf16 v[14:17], v[182:185], v[206:209], v[14:17]
	v_mfma_f32_16x16x32_bf16 v[6:9], v[174:177], v[214:217], v[6:9]
	v_mfma_f32_16x16x32_bf16 v[2:5], v[182:185], v[214:217], v[2:5]
	s_setprio 0
	s_barrier
	s_add_i32 s96, s96, 2
	s_add_u32 s66, s66, 0x100
	s_addc_u32 s67, s67, 0
	s_add_u32 s94, s94, 0x100
	s_addc_u32 s95, s95, 0
	s_cmp_gt_u32 s96, 5
	s_cbranch_scc0 .LBB0_560
	s_branch .Lrwp3a_exit
.Lrwp3a_prelaxed:
	s_waitcnt vmcnt(16)
	s_branch .Lrwp3a_pdone

.LBB0_572:
	v_ashrrev_i32_e32 v2, 31, v10
	v_lshrrev_b32_e32 v2, 26, v2
	v_add_u32_e32 v2, v10, v2
	v_ashrrev_i32_e32 v11, 6, v2
	v_bfe_i32 v2, v10, 27, 1
	v_lshlrev_b32_e32 v1, 4, v10
	v_lshrrev_b32_e32 v2, 22, v2
	v_add_u32_e32 v2, v1, v2
	v_and_b32_e32 v2, 0xfffffc00, v2
	v_sub_u32_e32 v2, v1, v2
	v_lshrrev_b32_e32 v3, 4, v2
	v_bitop3_b32 v2, v3, v2, 32 bitop3:0x6c
	v_ashrrev_i32_e32 v4, 31, v2
	v_lshrrev_b32_e32 v4, 26, v4
	v_add_u32_e32 v4, v2, v4
	v_lshlrev_b32_e32 v3, 3, v11
	v_ashrrev_i32_e32 v12, 6, v4
	v_and_b32_e32 v4, 0xc0, v4
	v_and_b32_e32 v3, -16, v3
	v_sub_u32_e32 v2, v2, v4
	v_mov_b32_e32 v4, 1
	v_add_u32_e32 v3, v12, v3
	v_ashrrev_i16_sdwa v2, v4, sext(v2) dst_sel:DWORD dst_unused:UNUSED_PAD src0_sel:DWORD src1_sel:BYTE_0
	s_ashr_i32 s0, s7, 3
	v_lshlrev_b32_e32 v5, 5, v11
	v_bfe_i32 v13, v2, 0, 16
	v_lshlrev_b32_e32 v2, 1, v3
	v_lshrrev_b32_e32 v6, 2, v3
	v_and_b32_e32 v7, 3, v12
	s_mov_b32 s7, 0x3fffe0
	v_and_b32_e32 v5, 32, v5
	v_and_b32_e32 v2, 24, v2
	v_and_b32_e32 v6, 4, v6
	v_and_or_b32 v7, v3, s7, v7
	v_or3_b32 v2, v7, v6, v2
	v_add_lshl_u32 v5, v5, v13, 1
	v_add_u32_e32 v1, 0x2000, v1
	v_lshl_add_u32 v132, v2, 10, v5
	v_ashrrev_i32_e32 v2, 31, v1
	v_lshrrev_b32_e32 v2, 22, v2
	s_add_i32 s0, s8, s0
	v_add_u32_e32 v2, v1, v2
	s_ashr_i32 s8, s0, 31
	v_ashrrev_i32_e32 v14, 10, v2
	s_lshr_b32 s8, s8, 27
	v_mul_i32_i24_e32 v2, 0x400, v14
	s_add_i32 s8, s0, s8
	v_sub_u32_e32 v1, v1, v2
	s_ashr_i32 s9, s8, 5
	s_andn2_b32 s8, s8, 31
	v_lshrrev_b32_e32 v2, 4, v1
	s_sub_i32 s8, s0, s8
	v_bitop3_b32 v1, v2, v1, 32 bitop3:0x6c
	s_bfe_i32 s0, s8, 0x80000
	v_lshl_add_u32 v130, v3, 10, v5
	v_ashrrev_i32_e32 v3, 31, v1
	s_bfe_u32 s0, s0, 0x3000c
	v_lshrrev_b32_e32 v3, 26, v3
	s_add_i32 s10, s8, s0
	v_add_u32_e32 v3, v1, v3
	s_bfe_i32 s0, s10, 0x80000
	s_and_b32 s10, s10, 0xf8
	v_lshlrev_b32_e32 v2, 3, v14
	v_ashrrev_i32_e32 v15, 6, v3
	v_and_b32_e32 v3, 0xc0, v3
	s_sub_i32 s8, s8, s10
	v_and_b32_e32 v2, -16, v2
	v_sub_u32_e32 v1, v1, v3
	s_lshl_b32 s9, s9, 3
	s_sext_i32_i16 s0, s0
	s_sext_i32_i8 s8, s8
	s_ashr_i32 s1, s6, 8
	v_add_u32_e32 v2, v15, v2
	v_ashrrev_i16_sdwa v1, v4, sext(v1) dst_sel:DWORD dst_unused:UNUSED_PAD src0_sel:DWORD src1_sel:BYTE_0
	v_and_b32_e32 v4, 3, v15
	s_lshr_b32 s0, s0, 3
	s_add_i32 s70, s9, s8
	v_and_or_b32 v4, v2, s7, v4
	s_ashr_i32 s7, s6, 6
	s_ashr_i32 s71, s70, 31
	s_bfe_i64 s[10:11], s[0:1], 0x100000
	s_lshl_b32 s31, s7, 10
	s_lshl_b64 s[8:9], s[70:71], 18
	s_lshl_b64 s[10:11], s[10:11], 18
	s_add_u32 s74, s40, s10
	v_lshlrev_b32_e32 v5, 5, v14
	v_bfe_i32 v16, v1, 0, 16
	v_lshlrev_b32_e32 v1, 1, v2
	v_lshrrev_b32_e32 v3, 2, v2
	s_addc_u32 s75, s41, s11
	s_add_i32 s71, s31, 0
	v_and_b32_e32 v5, 32, v5
	v_and_b32_e32 v1, 24, v1
	v_and_b32_e32 v3, 4, v3
	s_add_i32 m0, s71, 0x10000
	v_or3_b32 v1, v4, v3, v1
	v_add_lshl_u32 v3, v5, v16, 1
	global_load_lds_dwordx4 v132, s[74:75]
	s_add_i32 m0, s71, 0x12000
	v_lshl_add_u32 v136, v1, 10, v3
	s_add_u32 s10, s74, 0x20000
	global_load_lds_dwordx4 v136, s[74:75]
	s_addc_u32 s11, s75, 0
	s_add_i32 m0, s71, 0x14000
	v_lshl_add_u32 v134, v2, 10, v3
	global_load_lds_dwordx4 v132, s[10:11]
	s_add_i32 m0, s71, 0x16000
	s_add_u32 s72, s4, s8
	s_addc_u32 s73, s5, s9
	s_add_i32 s78, s71, 0x2000
	global_load_lds_dwordx4 v136, s[10:11]
	s_mov_b32 m0, s71
	s_add_u32 s8, s72, 0x20000
	global_load_lds_dwordx4 v130, s[72:73]
	s_mov_b32 m0, s78
	s_addc_u32 s9, s73, 0
	s_add_i32 s79, s71, 0x4000
	global_load_lds_dwordx4 v134, s[72:73]
	s_mov_b32 m0, s79
	s_add_i32 s80, s71, 0x6000
	global_load_lds_dwordx4 v130, s[8:9]
	s_mov_b32 m0, s80
	v_mov_b32_e32 v133, 0
	global_load_lds_dwordx4 v134, s[8:9]
	v_mov_b32_e32 v137, v133
	v_mov_b32_e32 v131, v133
	v_mov_b32_e32 v135, v133
	s_cmp_eq_u32 s1, 1
	s_mov_b32 s100, 0
	s_mov_b32 s81, 0
	v_lshl_add_u64 v[8:9], s[74:75], 0, v[132:133]
	v_lshl_add_u64 v[6:7], s[74:75], 0, v[136:137]
	v_lshl_add_u64 v[2:3], s[72:73], 0, v[130:131]
	s_cselect_b64 s[8:9], -1, 0
	s_cmp_lg_u32 s1, 1
	v_lshl_add_u64 v[4:5], s[72:73], 0, v[134:135]
	s_cbranch_scc1 .LBB0_574
	s_barrier

.LBB0_583:
	s_ashr_i32 s63, s62, 31
	s_lshl_b64 s[6:7], s[62:63], 18
	s_add_u32 s64, s4, s6
	s_addc_u32 s65, s5, s7
	s_and_b64 s[6:7], s[0:1], exec
	s_cselect_b32 s63, s65, s73
	s_cselect_b32 s90, s64, s72
	s_ashr_i32 s61, s60, 31
	s_lshl_b64 s[6:7], s[60:61], 18
	s_add_u32 s66, s40, s6
	s_addc_u32 s67, s41, s7
	s_and_b64 s[6:7], s[0:1], exec
	s_cselect_b32 s61, s67, s75
	s_cselect_b32 s91, s66, s74
	s_add_u32 s72, s72, 0x20080
	s_addc_u32 s73, s73, 0
	s_add_u32 s92, s74, 0x100
	v_mov_b32_e32 v2, 0
	s_addc_u32 s93, s75, 0
	s_mov_b32 s94, -2
	v_mov_b32_e32 v3, v2
	v_mov_b32_e32 v4, v2
	v_mov_b32_e32 v5, v2
	v_mov_b32_e32 v6, v2
	v_mov_b32_e32 v7, v2
	v_mov_b32_e32 v8, v2
	v_mov_b32_e32 v9, v2
	v_mov_b32_e32 v18, v2
	v_mov_b32_e32 v19, v2
	v_mov_b32_e32 v20, v2
	v_mov_b32_e32 v21, v2
	v_mov_b32_e32 v22, v2
	v_mov_b32_e32 v23, v2
	v_mov_b32_e32 v24, v2
	v_mov_b32_e32 v25, v2
	v_mov_b32_e32 v34, v2
	v_mov_b32_e32 v35, v2
	v_mov_b32_e32 v36, v2
	v_mov_b32_e32 v37, v2
	v_mov_b32_e32 v38, v2
	v_mov_b32_e32 v39, v2
	v_mov_b32_e32 v40, v2
	v_mov_b32_e32 v41, v2
	v_mov_b32_e32 v50, v2
	v_mov_b32_e32 v51, v2
	v_mov_b32_e32 v52, v2
	v_mov_b32_e32 v53, v2
	v_mov_b32_e32 v54, v2
	v_mov_b32_e32 v55, v2
	v_mov_b32_e32 v56, v2
	v_mov_b32_e32 v57, v2
	v_mov_b32_e32 v10, v2
	v_mov_b32_e32 v11, v2
	v_mov_b32_e32 v12, v2
	v_mov_b32_e32 v13, v2
	v_mov_b32_e32 v14, v2
	v_mov_b32_e32 v15, v2
	v_mov_b32_e32 v16, v2
	v_mov_b32_e32 v17, v2
	v_mov_b32_e32 v26, v2
	v_mov_b32_e32 v27, v2
	v_mov_b32_e32 v28, v2
	v_mov_b32_e32 v29, v2
	v_mov_b32_e32 v30, v2
	v_mov_b32_e32 v31, v2
	v_mov_b32_e32 v32, v2
	v_mov_b32_e32 v33, v2
	v_mov_b32_e32 v42, v2
	v_mov_b32_e32 v43, v2
	v_mov_b32_e32 v44, v2
	v_mov_b32_e32 v45, v2
	v_mov_b32_e32 v46, v2
	v_mov_b32_e32 v47, v2
	v_mov_b32_e32 v48, v2
	v_mov_b32_e32 v49, v2
	v_mov_b32_e32 v58, v2
	v_mov_b32_e32 v59, v2
	v_mov_b32_e32 v60, v2
	v_mov_b32_e32 v61, v2
	v_mov_b32_e32 v62, v2
	v_mov_b32_e32 v63, v2
	v_mov_b32_e32 v64, v2
	v_mov_b32_e32 v65, v2
	v_mov_b32_e32 v66, v2
	v_mov_b32_e32 v67, v2
	v_mov_b32_e32 v68, v2
	v_mov_b32_e32 v69, v2
	v_mov_b32_e32 v70, v2
	v_mov_b32_e32 v71, v2
	v_mov_b32_e32 v72, v2
	v_mov_b32_e32 v73, v2
	v_mov_b32_e32 v82, v2
	v_mov_b32_e32 v83, v2
	v_mov_b32_e32 v84, v2
	v_mov_b32_e32 v85, v2
	v_mov_b32_e32 v86, v2
	v_mov_b32_e32 v87, v2
	v_mov_b32_e32 v88, v2
	v_mov_b32_e32 v89, v2
	s_cmp_eq_u32 s100, 1
	s_cbranch_scc1 .Lrwp3b_prelaxed
	s_waitcnt vmcnt(0)
.Lrwp3b_pdone:
	v_mov_b32_e32 v98, v2
	v_mov_b32_e32 v99, v2
	v_mov_b32_e32 v100, v2
	v_mov_b32_e32 v101, v2
	v_mov_b32_e32 v102, v2
	v_mov_b32_e32 v103, v2
	v_mov_b32_e32 v104, v2
	v_mov_b32_e32 v105, v2
	v_mov_b32_e32 v114, v2
	v_mov_b32_e32 v115, v2
	v_mov_b32_e32 v116, v2
	v_mov_b32_e32 v117, v2
	v_mov_b32_e32 v118, v2
	v_mov_b32_e32 v119, v2
	v_mov_b32_e32 v120, v2
	v_mov_b32_e32 v121, v2
	v_mov_b32_e32 v74, v2
	v_mov_b32_e32 v75, v2
	v_mov_b32_e32 v76, v2
	v_mov_b32_e32 v77, v2
	v_mov_b32_e32 v78, v2
	v_mov_b32_e32 v79, v2
	v_mov_b32_e32 v80, v2
	v_mov_b32_e32 v81, v2
	v_mov_b32_e32 v90, v2
	v_mov_b32_e32 v91, v2
	v_mov_b32_e32 v92, v2
	v_mov_b32_e32 v93, v2
	v_mov_b32_e32 v94, v2
	v_mov_b32_e32 v95, v2
	v_mov_b32_e32 v96, v2
	v_mov_b32_e32 v97, v2
	v_mov_b32_e32 v106, v2
	v_mov_b32_e32 v107, v2
	v_mov_b32_e32 v108, v2
	v_mov_b32_e32 v109, v2
	v_mov_b32_e32 v110, v2
	v_mov_b32_e32 v111, v2
	v_mov_b32_e32 v112, v2
	v_mov_b32_e32 v113, v2
	v_mov_b32_e32 v122, v2
	v_mov_b32_e32 v123, v2
	v_mov_b32_e32 v124, v2
	v_mov_b32_e32 v125, v2
	v_mov_b32_e32 v126, v2
	v_mov_b32_e32 v127, v2
	v_mov_b32_e32 v128, v2
	v_mov_b32_e32 v129, v2
	s_cmp_lg_u32 s100, 0
	s_cbranch_scc1 .Lrwp3b_first

.Lrwp3b_exit:
	s_and_b64 vcc, exec, s[42:43]
	s_cbranch_vccz .LBB0_587
	s_barrier
.LBB0_587:
	s_lshl_b32 s98, s70, 8
	s_add_i32 s98, s98, s82
	s_lshl_b32 s98, s98, 11
	s_lshl_b32 s99, s89, 8
	s_or_b32 s99, s99, s83
	s_lshl_b32 s99, s99, 1
	s_add_u32 s98, s98, s99
	s_add_u32 s98, s44, s98
	s_addc_u32 s99, s45, 0
	v_lshlrev_b32_e32 v146, 11, v1
	v_lshl_add_u32 v146, v148, 4, v146
	v_add_u32_e32 v147, 0x8000000, v146
	global_load_dwordx4 v[154:157], v146, s[98:99]
	global_load_dwordx4 v[158:161], v147, s[98:99]
	global_load_dwordx4 v[162:165], v146, s[98:99] offset:256
	global_load_dwordx4 v[166:169], v147, s[98:99] offset:256
	s_add_u32 s98, s98, 0x8000
	s_addc_u32 s99, s99, 0
	global_load_dwordx4 v[170:173], v146, s[98:99]
	global_load_dwordx4 v[174:177], v147, s[98:99]
	global_load_dwordx4 v[178:181], v146, s[98:99] offset:256
	global_load_dwordx4 v[182:185], v147, s[98:99] offset:256
	s_add_u32 s98, s98, 0x8000
	s_addc_u32 s99, s99, 0
	global_load_dwordx4 v[186:189], v146, s[98:99]
	global_load_dwordx4 v[190:193], v147, s[98:99]
	global_load_dwordx4 v[194:197], v146, s[98:99] offset:256
	global_load_dwordx4 v[198:201], v147, s[98:99] offset:256
	s_add_u32 s98, s98, 0x8000
	s_addc_u32 s99, s99, 0
	global_load_dwordx4 v[202:205], v146, s[98:99]
	global_load_dwordx4 v[206:209], v147, s[98:99]
	global_load_dwordx4 v[210:213], v146, s[98:99] offset:256
	global_load_dwordx4 v[214:217], v147, s[98:99] offset:256
	s_waitcnt vmcnt(14)
	v_lshlrev_b32_e32 v218, 16, v154
	v_and_b32_e32 v154, 0xffff0000, v154
	v_lshlrev_b32_e32 v219, 16, v155
	v_and_b32_e32 v155, 0xffff0000, v155
	v_lshlrev_b32_e32 v220, 16, v156
	v_and_b32_e32 v156, 0xffff0000, v156
	v_lshlrev_b32_e32 v221, 16, v157
	v_and_b32_e32 v157, 0xffff0000, v157
	v_lshlrev_b32_e32 v222, 16, v158
	v_and_b32_e32 v158, 0xffff0000, v158
	v_lshlrev_b32_e32 v223, 16, v159
	v_and_b32_e32 v159, 0xffff0000, v159
	v_lshlrev_b32_e32 v224, 16, v160
	v_and_b32_e32 v160, 0xffff0000, v160
	v_lshlrev_b32_e32 v225, 16, v161
	v_and_b32_e32 v161, 0xffff0000, v161
	v_fmac_f32_e32 v218, v126, v222
	v_fmac_f32_e32 v154, v127, v158
	v_fmac_f32_e32 v219, v128, v223
	v_fmac_f32_e32 v155, v129, v159
	v_fmac_f32_e32 v220, v122, v224
	v_fmac_f32_e32 v156, v123, v160
	v_fmac_f32_e32 v221, v124, v225
	v_fmac_f32_e32 v157, v125, v161
	v_cvt_pk_bf16_f32 v158, v218, v154
	v_cvt_pk_bf16_f32 v159, v219, v155
	v_cvt_pk_bf16_f32 v160, v220, v156
	v_cvt_pk_bf16_f32 v161, v221, v157
	s_sub_u32 s98, s98, 0x18000
	s_subb_u32 s99, s99, 0
	global_store_dwordx4 v146, v[158:161], s[98:99] nt
	s_waitcnt vmcnt(13)
	v_lshlrev_b32_e32 v218, 16, v162
	v_and_b32_e32 v162, 0xffff0000, v162
	v_lshlrev_b32_e32 v219, 16, v163
	v_and_b32_e32 v163, 0xffff0000, v163
	v_lshlrev_b32_e32 v220, 16, v164
	v_and_b32_e32 v164, 0xffff0000, v164
	v_lshlrev_b32_e32 v221, 16, v165
	v_and_b32_e32 v165, 0xffff0000, v165
	v_lshlrev_b32_e32 v222, 16, v166
	v_and_b32_e32 v166, 0xffff0000, v166
	v_lshlrev_b32_e32 v223, 16, v167
	v_and_b32_e32 v167, 0xffff0000, v167
	v_lshlrev_b32_e32 v224, 16, v168
	v_and_b32_e32 v168, 0xffff0000, v168
	v_lshlrev_b32_e32 v225, 16, v169
	v_and_b32_e32 v169, 0xffff0000, v169
	v_fmac_f32_e32 v218, v118, v222
	v_fmac_f32_e32 v162, v119, v166
	v_fmac_f32_e32 v219, v120, v223
	v_fmac_f32_e32 v163, v121, v167
	v_fmac_f32_e32 v220, v114, v224
	v_fmac_f32_e32 v164, v115, v168
	v_fmac_f32_e32 v221, v116, v225
	v_fmac_f32_e32 v165, v117, v169
	v_cvt_pk_bf16_f32 v166, v218, v162
	v_cvt_pk_bf16_f32 v167, v219, v163
	v_cvt_pk_bf16_f32 v168, v220, v164
	v_cvt_pk_bf16_f32 v169, v221, v165
	global_store_dwordx4 v146, v[166:169], s[98:99] offset:256 nt
	s_waitcnt vmcnt(12)
	v_lshlrev_b32_e32 v218, 16, v170
	v_and_b32_e32 v170, 0xffff0000, v170
	v_lshlrev_b32_e32 v219, 16, v171
	v_and_b32_e32 v171, 0xffff0000, v171
	v_lshlrev_b32_e32 v220, 16, v172
	v_and_b32_e32 v172, 0xffff0000, v172
	v_lshlrev_b32_e32 v221, 16, v173
	v_and_b32_e32 v173, 0xffff0000, v173
	v_lshlrev_b32_e32 v222, 16, v174
	v_and_b32_e32 v174, 0xffff0000, v174
	v_lshlrev_b32_e32 v223, 16, v175
	v_and_b32_e32 v175, 0xffff0000, v175
	v_lshlrev_b32_e32 v224, 16, v176
	v_and_b32_e32 v176, 0xffff0000, v176
	v_lshlrev_b32_e32 v225, 16, v177
	v_and_b32_e32 v177, 0xffff0000, v177
	v_fmac_f32_e32 v218, v110, v222
	v_fmac_f32_e32 v170, v111, v174
	v_fmac_f32_e32 v219, v112, v223
	v_fmac_f32_e32 v171, v113, v175
	v_fmac_f32_e32 v220, v106, v224
	v_fmac_f32_e32 v172, v107, v176
	v_fmac_f32_e32 v221, v108, v225
	v_fmac_f32_e32 v173, v109, v177
	v_cvt_pk_bf16_f32 v174, v218, v170
	v_cvt_pk_bf16_f32 v175, v219, v171
	v_cvt_pk_bf16_f32 v176, v220, v172
	v_cvt_pk_bf16_f32 v177, v221, v173
	s_add_u32 s98, s98, 0x8000
	s_addc_u32 s99, s99, 0
	global_store_dwordx4 v146, v[174:177], s[98:99] nt
	s_waitcnt vmcnt(11)
	v_lshlrev_b32_e32 v218, 16, v178
	v_and_b32_e32 v178, 0xffff0000, v178
	v_lshlrev_b32_e32 v219, 16, v179
	v_and_b32_e32 v179, 0xffff0000, v179
	v_lshlrev_b32_e32 v220, 16, v180
	v_and_b32_e32 v180, 0xffff0000, v180
	v_lshlrev_b32_e32 v221, 16, v181
	v_and_b32_e32 v181, 0xffff0000, v181
	v_lshlrev_b32_e32 v222, 16, v182
	v_and_b32_e32 v182, 0xffff0000, v182
	v_lshlrev_b32_e32 v223, 16, v183
	v_and_b32_e32 v183, 0xffff0000, v183
	v_lshlrev_b32_e32 v224, 16, v184
	v_and_b32_e32 v184, 0xffff0000, v184
	v_lshlrev_b32_e32 v225, 16, v185
	v_and_b32_e32 v185, 0xffff0000, v185
	v_fmac_f32_e32 v218, v102, v222
	v_fmac_f32_e32 v178, v103, v182
	v_fmac_f32_e32 v219, v104, v223
	v_fmac_f32_e32 v179, v105, v183
	v_fmac_f32_e32 v220, v98, v224
	v_fmac_f32_e32 v180, v99, v184
	v_fmac_f32_e32 v221, v100, v225
	v_fmac_f32_e32 v181, v101, v185
	v_cvt_pk_bf16_f32 v182, v218, v178
	v_cvt_pk_bf16_f32 v183, v219, v179
	v_cvt_pk_bf16_f32 v184, v220, v180
	v_cvt_pk_bf16_f32 v185, v221, v181
	global_store_dwordx4 v146, v[182:185], s[98:99] offset:256 nt
	s_waitcnt vmcnt(10)
	v_lshlrev_b32_e32 v218, 16, v186
	v_and_b32_e32 v186, 0xffff0000, v186
	v_lshlrev_b32_e32 v219, 16, v187
	v_and_b32_e32 v187, 0xffff0000, v187
	v_lshlrev_b32_e32 v220, 16, v188
	v_and_b32_e32 v188, 0xffff0000, v188
	v_lshlrev_b32_e32 v221, 16, v189
	v_and_b32_e32 v189, 0xffff0000, v189
	v_lshlrev_b32_e32 v222, 16, v190
	v_and_b32_e32 v190, 0xffff0000, v190
	v_lshlrev_b32_e32 v223, 16, v191
	v_and_b32_e32 v191, 0xffff0000, v191
	v_lshlrev_b32_e32 v224, 16, v192
	v_and_b32_e32 v192, 0xffff0000, v192
	v_lshlrev_b32_e32 v225, 16, v193
	v_and_b32_e32 v193, 0xffff0000, v193
	v_fmac_f32_e32 v218, v94, v222
	v_fmac_f32_e32 v186, v95, v190
	v_fmac_f32_e32 v219, v96, v223
	v_fmac_f32_e32 v187, v97, v191
	v_fmac_f32_e32 v220, v90, v224
	v_fmac_f32_e32 v188, v91, v192
	v_fmac_f32_e32 v221, v92, v225
	v_fmac_f32_e32 v189, v93, v193
	v_cvt_pk_bf16_f32 v190, v218, v186
	v_cvt_pk_bf16_f32 v191, v219, v187
	v_cvt_pk_bf16_f32 v192, v220, v188
	v_cvt_pk_bf16_f32 v193, v221, v189
	s_add_u32 s98, s98, 0x8000
	s_addc_u32 s99, s99, 0
	global_store_dwordx4 v146, v[190:193], s[98:99] nt
	s_waitcnt vmcnt(9)
	v_lshlrev_b32_e32 v218, 16, v194
	v_and_b32_e32 v194, 0xffff0000, v194
	v_lshlrev_b32_e32 v219, 16, v195
	v_and_b32_e32 v195, 0xffff0000, v195
	v_lshlrev_b32_e32 v220, 16, v196
	v_and_b32_e32 v196, 0xffff0000, v196
	v_lshlrev_b32_e32 v221, 16, v197
	v_and_b32_e32 v197, 0xffff0000, v197
	v_lshlrev_b32_e32 v222, 16, v198
	v_and_b32_e32 v198, 0xffff0000, v198
	v_lshlrev_b32_e32 v223, 16, v199
	v_and_b32_e32 v199, 0xffff0000, v199
	v_lshlrev_b32_e32 v224, 16, v200
	v_and_b32_e32 v200, 0xffff0000, v200
	v_lshlrev_b32_e32 v225, 16, v201
	v_and_b32_e32 v201, 0xffff0000, v201
	v_fmac_f32_e32 v218, v86, v222
	v_fmac_f32_e32 v194, v87, v198
	v_fmac_f32_e32 v219, v88, v223
	v_fmac_f32_e32 v195, v89, v199
	v_fmac_f32_e32 v220, v82, v224
	v_fmac_f32_e32 v196, v83, v200
	v_fmac_f32_e32 v221, v84, v225
	v_fmac_f32_e32 v197, v85, v201
	v_cvt_pk_bf16_f32 v198, v218, v194
	v_cvt_pk_bf16_f32 v199, v219, v195
	v_cvt_pk_bf16_f32 v200, v220, v196
	v_cvt_pk_bf16_f32 v201, v221, v197
	global_store_dwordx4 v146, v[198:201], s[98:99] offset:256 nt
	s_waitcnt vmcnt(8)
	v_lshlrev_b32_e32 v218, 16, v202
	v_and_b32_e32 v202, 0xffff0000, v202
	v_lshlrev_b32_e32 v219, 16, v203
	v_and_b32_e32 v203, 0xffff0000, v203
	v_lshlrev_b32_e32 v220, 16, v204
	v_and_b32_e32 v204, 0xffff0000, v204
	v_lshlrev_b32_e32 v221, 16, v205
	v_and_b32_e32 v205, 0xffff0000, v205
	v_lshlrev_b32_e32 v222, 16, v206
	v_and_b32_e32 v206, 0xffff0000, v206
	v_lshlrev_b32_e32 v223, 16, v207
	v_and_b32_e32 v207, 0xffff0000, v207
	v_lshlrev_b32_e32 v224, 16, v208
	v_and_b32_e32 v208, 0xffff0000, v208
	v_lshlrev_b32_e32 v225, 16, v209
	v_and_b32_e32 v209, 0xffff0000, v209
	v_fmac_f32_e32 v218, v78, v222
	v_fmac_f32_e32 v202, v79, v206
	v_fmac_f32_e32 v219, v80, v223
	v_fmac_f32_e32 v203, v81, v207
	v_fmac_f32_e32 v220, v74, v224
	v_fmac_f32_e32 v204, v75, v208
	v_fmac_f32_e32 v221, v76, v225
	v_fmac_f32_e32 v205, v77, v209
	v_cvt_pk_bf16_f32 v206, v218, v202
	v_cvt_pk_bf16_f32 v207, v219, v203
	v_cvt_pk_bf16_f32 v208, v220, v204
	v_cvt_pk_bf16_f32 v209, v221, v205
	s_add_u32 s98, s98, 0x8000
	s_addc_u32 s99, s99, 0
	global_store_dwordx4 v146, v[206:209], s[98:99] nt
	s_waitcnt vmcnt(7)
	v_lshlrev_b32_e32 v218, 16, v210
	v_and_b32_e32 v210, 0xffff0000, v210
	v_lshlrev_b32_e32 v219, 16, v211
	v_and_b32_e32 v211, 0xffff0000, v211
	v_lshlrev_b32_e32 v220, 16, v212
	v_and_b32_e32 v212, 0xffff0000, v212
	v_lshlrev_b32_e32 v221, 16, v213
	v_and_b32_e32 v213, 0xffff0000, v213
	v_lshlrev_b32_e32 v222, 16, v214
	v_and_b32_e32 v214, 0xffff0000, v214
	v_lshlrev_b32_e32 v223, 16, v215
	v_and_b32_e32 v215, 0xffff0000, v215
	v_lshlrev_b32_e32 v224, 16, v216
	v_and_b32_e32 v216, 0xffff0000, v216
	v_lshlrev_b32_e32 v225, 16, v217
	v_and_b32_e32 v217, 0xffff0000, v217
	v_fmac_f32_e32 v218, v70, v222
	v_fmac_f32_e32 v210, v71, v214
	v_fmac_f32_e32 v219, v72, v223
	v_fmac_f32_e32 v211, v73, v215
	v_fmac_f32_e32 v220, v66, v224
	v_fmac_f32_e32 v212, v67, v216
	v_fmac_f32_e32 v221, v68, v225
	v_fmac_f32_e32 v213, v69, v217
	v_cvt_pk_bf16_f32 v214, v218, v210
	v_cvt_pk_bf16_f32 v215, v219, v211
	v_cvt_pk_bf16_f32 v216, v220, v212
	v_cvt_pk_bf16_f32 v217, v221, v213
	global_store_dwordx4 v146, v[214:217], s[98:99] offset:256 nt
	s_add_u32 s98, s98, 0x28000
	s_addc_u32 s99, s99, 0
	global_load_dwordx4 v[154:157], v146, s[98:99]
	global_load_dwordx4 v[158:161], v147, s[98:99]
	global_load_dwordx4 v[162:165], v146, s[98:99] offset:256
	global_load_dwordx4 v[166:169], v147, s[98:99] offset:256
	s_add_u32 s98, s98, 0x8000
	s_addc_u32 s99, s99, 0
	global_load_dwordx4 v[170:173], v146, s[98:99]
	global_load_dwordx4 v[174:177], v147, s[98:99]
	global_load_dwordx4 v[178:181], v146, s[98:99] offset:256
	global_load_dwordx4 v[182:185], v147, s[98:99] offset:256
	s_add_u32 s98, s98, 0x8000
	s_addc_u32 s99, s99, 0
	global_load_dwordx4 v[186:189], v146, s[98:99]
	global_load_dwordx4 v[190:193], v147, s[98:99]
	global_load_dwordx4 v[194:197], v146, s[98:99] offset:256
	global_load_dwordx4 v[198:201], v147, s[98:99] offset:256
	s_add_u32 s98, s98, 0x8000
	s_addc_u32 s99, s99, 0
	global_load_dwordx4 v[202:205], v146, s[98:99]
	global_load_dwordx4 v[206:209], v147, s[98:99]
	global_load_dwordx4 v[210:213], v146, s[98:99] offset:256
	global_load_dwordx4 v[214:217], v147, s[98:99] offset:256
	s_waitcnt vmcnt(14)
	v_lshlrev_b32_e32 v218, 16, v154
	v_and_b32_e32 v154, 0xffff0000, v154
	v_lshlrev_b32_e32 v219, 16, v155
	v_and_b32_e32 v155, 0xffff0000, v155
	v_lshlrev_b32_e32 v220, 16, v156
	v_and_b32_e32 v156, 0xffff0000, v156
	v_lshlrev_b32_e32 v221, 16, v157
	v_and_b32_e32 v157, 0xffff0000, v157
	v_lshlrev_b32_e32 v222, 16, v158
	v_and_b32_e32 v158, 0xffff0000, v158
	v_lshlrev_b32_e32 v223, 16, v159
	v_and_b32_e32 v159, 0xffff0000, v159
	v_lshlrev_b32_e32 v224, 16, v160
	v_and_b32_e32 v160, 0xffff0000, v160
	v_lshlrev_b32_e32 v225, 16, v161
	v_and_b32_e32 v161, 0xffff0000, v161
	v_fmac_f32_e32 v218, v62, v222
	v_fmac_f32_e32 v154, v63, v158
	v_fmac_f32_e32 v219, v64, v223
	v_fmac_f32_e32 v155, v65, v159
	v_fmac_f32_e32 v220, v58, v224
	v_fmac_f32_e32 v156, v59, v160
	v_fmac_f32_e32 v221, v60, v225
	v_fmac_f32_e32 v157, v61, v161
	v_cvt_pk_bf16_f32 v158, v218, v154
	v_cvt_pk_bf16_f32 v159, v219, v155
	v_cvt_pk_bf16_f32 v160, v220, v156
	v_cvt_pk_bf16_f32 v161, v221, v157
	s_sub_u32 s98, s98, 0x18000
	s_subb_u32 s99, s99, 0
	global_store_dwordx4 v146, v[158:161], s[98:99] nt
	s_waitcnt vmcnt(13)
	v_lshlrev_b32_e32 v218, 16, v162
	v_and_b32_e32 v162, 0xffff0000, v162
	v_lshlrev_b32_e32 v219, 16, v163
	v_and_b32_e32 v163, 0xffff0000, v163
	v_lshlrev_b32_e32 v220, 16, v164
	v_and_b32_e32 v164, 0xffff0000, v164
	v_lshlrev_b32_e32 v221, 16, v165
	v_and_b32_e32 v165, 0xffff0000, v165
	v_lshlrev_b32_e32 v222, 16, v166
	v_and_b32_e32 v166, 0xffff0000, v166
	v_lshlrev_b32_e32 v223, 16, v167
	v_and_b32_e32 v167, 0xffff0000, v167
	v_lshlrev_b32_e32 v224, 16, v168
	v_and_b32_e32 v168, 0xffff0000, v168
	v_lshlrev_b32_e32 v225, 16, v169
	v_and_b32_e32 v169, 0xffff0000, v169
	v_fmac_f32_e32 v218, v54, v222
	v_fmac_f32_e32 v162, v55, v166
	v_fmac_f32_e32 v219, v56, v223
	v_fmac_f32_e32 v163, v57, v167
	v_fmac_f32_e32 v220, v50, v224
	v_fmac_f32_e32 v164, v51, v168
	v_fmac_f32_e32 v221, v52, v225
	v_fmac_f32_e32 v165, v53, v169
	v_cvt_pk_bf16_f32 v166, v218, v162
	v_cvt_pk_bf16_f32 v167, v219, v163
	v_cvt_pk_bf16_f32 v168, v220, v164
	v_cvt_pk_bf16_f32 v169, v221, v165
	global_store_dwordx4 v146, v[166:169], s[98:99] offset:256 nt
	s_waitcnt vmcnt(12)
	v_lshlrev_b32_e32 v218, 16, v170
	v_and_b32_e32 v170, 0xffff0000, v170
	v_lshlrev_b32_e32 v219, 16, v171
	v_and_b32_e32 v171, 0xffff0000, v171
	v_lshlrev_b32_e32 v220, 16, v172
	v_and_b32_e32 v172, 0xffff0000, v172
	v_lshlrev_b32_e32 v221, 16, v173
	v_and_b32_e32 v173, 0xffff0000, v173
	v_lshlrev_b32_e32 v222, 16, v174
	v_and_b32_e32 v174, 0xffff0000, v174
	v_lshlrev_b32_e32 v223, 16, v175
	v_and_b32_e32 v175, 0xffff0000, v175
	v_lshlrev_b32_e32 v224, 16, v176
	v_and_b32_e32 v176, 0xffff0000, v176
	v_lshlrev_b32_e32 v225, 16, v177
	v_and_b32_e32 v177, 0xffff0000, v177
	v_fmac_f32_e32 v218, v46, v222
	v_fmac_f32_e32 v170, v47, v174
	v_fmac_f32_e32 v219, v48, v223
	v_fmac_f32_e32 v171, v49, v175
	v_fmac_f32_e32 v220, v42, v224
	v_fmac_f32_e32 v172, v43, v176
	v_fmac_f32_e32 v221, v44, v225
	v_fmac_f32_e32 v173, v45, v177
	v_cvt_pk_bf16_f32 v174, v218, v170
	v_cvt_pk_bf16_f32 v175, v219, v171
	v_cvt_pk_bf16_f32 v176, v220, v172
	v_cvt_pk_bf16_f32 v177, v221, v173
	s_add_u32 s98, s98, 0x8000
	s_addc_u32 s99, s99, 0
	global_store_dwordx4 v146, v[174:177], s[98:99] nt
	s_waitcnt vmcnt(11)
	v_lshlrev_b32_e32 v218, 16, v178
	v_and_b32_e32 v178, 0xffff0000, v178
	v_lshlrev_b32_e32 v219, 16, v179
	v_and_b32_e32 v179, 0xffff0000, v179
	v_lshlrev_b32_e32 v220, 16, v180
	v_and_b32_e32 v180, 0xffff0000, v180
	v_lshlrev_b32_e32 v221, 16, v181
	v_and_b32_e32 v181, 0xffff0000, v181
	v_lshlrev_b32_e32 v222, 16, v182
	v_and_b32_e32 v182, 0xffff0000, v182
	v_lshlrev_b32_e32 v223, 16, v183
	v_and_b32_e32 v183, 0xffff0000, v183
	v_lshlrev_b32_e32 v224, 16, v184
	v_and_b32_e32 v184, 0xffff0000, v184
	v_lshlrev_b32_e32 v225, 16, v185
	v_and_b32_e32 v185, 0xffff0000, v185
	v_fmac_f32_e32 v218, v38, v222
	v_fmac_f32_e32 v178, v39, v182
	v_fmac_f32_e32 v219, v40, v223
	v_fmac_f32_e32 v179, v41, v183
	v_fmac_f32_e32 v220, v34, v224
	v_fmac_f32_e32 v180, v35, v184
	v_fmac_f32_e32 v221, v36, v225
	v_fmac_f32_e32 v181, v37, v185
	v_cvt_pk_bf16_f32 v182, v218, v178
	v_cvt_pk_bf16_f32 v183, v219, v179
	v_cvt_pk_bf16_f32 v184, v220, v180
	v_cvt_pk_bf16_f32 v185, v221, v181
	global_store_dwordx4 v146, v[182:185], s[98:99] offset:256 nt
	s_waitcnt vmcnt(10)
	v_lshlrev_b32_e32 v218, 16, v186
	v_and_b32_e32 v186, 0xffff0000, v186
	v_lshlrev_b32_e32 v219, 16, v187
	v_and_b32_e32 v187, 0xffff0000, v187
	v_lshlrev_b32_e32 v220, 16, v188
	v_and_b32_e32 v188, 0xffff0000, v188
	v_lshlrev_b32_e32 v221, 16, v189
	v_and_b32_e32 v189, 0xffff0000, v189
	v_lshlrev_b32_e32 v222, 16, v190
	v_and_b32_e32 v190, 0xffff0000, v190
	v_lshlrev_b32_e32 v223, 16, v191
	v_and_b32_e32 v191, 0xffff0000, v191
	v_lshlrev_b32_e32 v224, 16, v192
	v_and_b32_e32 v192, 0xffff0000, v192
	v_lshlrev_b32_e32 v225, 16, v193
	v_and_b32_e32 v193, 0xffff0000, v193
	v_fmac_f32_e32 v218, v30, v222
	v_fmac_f32_e32 v186, v31, v190
	v_fmac_f32_e32 v219, v32, v223
	v_fmac_f32_e32 v187, v33, v191
	v_fmac_f32_e32 v220, v26, v224
	v_fmac_f32_e32 v188, v27, v192
	v_fmac_f32_e32 v221, v28, v225
	v_fmac_f32_e32 v189, v29, v193
	v_cvt_pk_bf16_f32 v190, v218, v186
	v_cvt_pk_bf16_f32 v191, v219, v187
	v_cvt_pk_bf16_f32 v192, v220, v188
	v_cvt_pk_bf16_f32 v193, v221, v189
	s_add_u32 s98, s98, 0x8000
	s_addc_u32 s99, s99, 0
	global_store_dwordx4 v146, v[190:193], s[98:99] nt
	s_waitcnt vmcnt(9)
	v_lshlrev_b32_e32 v218, 16, v194
	v_and_b32_e32 v194, 0xffff0000, v194
	v_lshlrev_b32_e32 v219, 16, v195
	v_and_b32_e32 v195, 0xffff0000, v195
	v_lshlrev_b32_e32 v220, 16, v196
	v_and_b32_e32 v196, 0xffff0000, v196
	v_lshlrev_b32_e32 v221, 16, v197
	v_and_b32_e32 v197, 0xffff0000, v197
	v_lshlrev_b32_e32 v222, 16, v198
	v_and_b32_e32 v198, 0xffff0000, v198
	v_lshlrev_b32_e32 v223, 16, v199
	v_and_b32_e32 v199, 0xffff0000, v199
	v_lshlrev_b32_e32 v224, 16, v200
	v_and_b32_e32 v200, 0xffff0000, v200
	v_lshlrev_b32_e32 v225, 16, v201
	v_and_b32_e32 v201, 0xffff0000, v201
	v_fmac_f32_e32 v218, v22, v222
	v_fmac_f32_e32 v194, v23, v198
	v_fmac_f32_e32 v219, v24, v223
	v_fmac_f32_e32 v195, v25, v199
	v_fmac_f32_e32 v220, v18, v224
	v_fmac_f32_e32 v196, v19, v200
	v_fmac_f32_e32 v221, v20, v225
	v_fmac_f32_e32 v197, v21, v201
	v_cvt_pk_bf16_f32 v198, v218, v194
	v_cvt_pk_bf16_f32 v199, v219, v195
	v_cvt_pk_bf16_f32 v200, v220, v196
	v_cvt_pk_bf16_f32 v201, v221, v197
	global_store_dwordx4 v146, v[198:201], s[98:99] offset:256 nt
	s_waitcnt vmcnt(8)
	v_lshlrev_b32_e32 v218, 16, v202
	v_and_b32_e32 v202, 0xffff0000, v202
	v_lshlrev_b32_e32 v219, 16, v203
	v_and_b32_e32 v203, 0xffff0000, v203
	v_lshlrev_b32_e32 v220, 16, v204
	v_and_b32_e32 v204, 0xffff0000, v204
	v_lshlrev_b32_e32 v221, 16, v205
	v_and_b32_e32 v205, 0xffff0000, v205
	v_lshlrev_b32_e32 v222, 16, v206
	v_and_b32_e32 v206, 0xffff0000, v206
	v_lshlrev_b32_e32 v223, 16, v207
	v_and_b32_e32 v207, 0xffff0000, v207
	v_lshlrev_b32_e32 v224, 16, v208
	v_and_b32_e32 v208, 0xffff0000, v208
	v_lshlrev_b32_e32 v225, 16, v209
	v_and_b32_e32 v209, 0xffff0000, v209
	v_fmac_f32_e32 v218, v14, v222
	v_fmac_f32_e32 v202, v15, v206
	v_fmac_f32_e32 v219, v16, v223
	v_fmac_f32_e32 v203, v17, v207
	v_fmac_f32_e32 v220, v10, v224
	v_fmac_f32_e32 v204, v11, v208
	v_fmac_f32_e32 v221, v12, v225
	v_fmac_f32_e32 v205, v13, v209
	v_cvt_pk_bf16_f32 v206, v218, v202
	v_cvt_pk_bf16_f32 v207, v219, v203
	v_cvt_pk_bf16_f32 v208, v220, v204
	v_cvt_pk_bf16_f32 v209, v221, v205
	s_add_u32 s98, s98, 0x8000
	s_addc_u32 s99, s99, 0
	global_store_dwordx4 v146, v[206:209], s[98:99] nt
	s_waitcnt vmcnt(7)
	v_lshlrev_b32_e32 v218, 16, v210
	v_and_b32_e32 v210, 0xffff0000, v210
	v_lshlrev_b32_e32 v219, 16, v211
	v_and_b32_e32 v211, 0xffff0000, v211
	v_lshlrev_b32_e32 v220, 16, v212
	v_and_b32_e32 v212, 0xffff0000, v212
	v_lshlrev_b32_e32 v221, 16, v213
	v_and_b32_e32 v213, 0xffff0000, v213
	v_lshlrev_b32_e32 v222, 16, v214
	v_and_b32_e32 v214, 0xffff0000, v214
	v_lshlrev_b32_e32 v223, 16, v215
	v_and_b32_e32 v215, 0xffff0000, v215
	v_lshlrev_b32_e32 v224, 16, v216
	v_and_b32_e32 v216, 0xffff0000, v216
	v_lshlrev_b32_e32 v225, 16, v217
	v_and_b32_e32 v217, 0xffff0000, v217
	v_fmac_f32_e32 v218, v6, v222
	v_fmac_f32_e32 v210, v7, v214
	v_fmac_f32_e32 v219, v8, v223
	v_fmac_f32_e32 v211, v9, v215
	v_fmac_f32_e32 v220, v2, v224
	v_fmac_f32_e32 v212, v3, v216
	v_fmac_f32_e32 v221, v4, v225
	v_fmac_f32_e32 v213, v5, v217
	v_cvt_pk_bf16_f32 v214, v218, v210
	v_cvt_pk_bf16_f32 v215, v219, v211
	v_cvt_pk_bf16_f32 v216, v220, v212
	v_cvt_pk_bf16_f32 v217, v221, v213
	global_store_dwordx4 v146, v[214:217], s[98:99] offset:256 nt
	s_andn2_b64 vcc, exec, s[0:1]
	s_mov_b64 s[0:1], -1
	s_mov_b32 s100, 1
	s_cbranch_vccnz .LBB0_576
	s_andn2_b64 vcc, exec, s[8:9]
	s_cbranch_vccnz .LBB0_575
	s_barrier
	s_branch .LBB0_575
.Lrwp3b_first:
	ds_read_b128 v[154:157], v150
	ds_read_b128 v[158:161], v150 offset:1024
	ds_read_b128 v[162:165], v150 offset:2048
	ds_read_b128 v[166:169], v150 offset:3072
	ds_read_b128 v[170:173], v151
	ds_read_b128 v[174:177], v151 offset:1024
	ds_read_b128 v[178:181], v151 offset:2048
	ds_read_b128 v[182:185], v151 offset:3072
	s_add_u32 s6, s72, 0xfffe0080
	s_addc_u32 s7, s73, -1
	s_cmp_eq_u32 s94, 4
	s_cselect_b32 s77, s63, s7
	s_cselect_b32 s76, s90, s6
	s_cselect_b32 s75, s61, s93
	s_cselect_b32 s74, s91, s92
	v_lshl_add_u64 v[146:147], s[72:73], 0, v[138:139]
	s_add_i32 m0, s71, 0xc000
	ds_read_b128 v[186:189], v152
	ds_read_b128 v[190:193], v152 offset:1024
	ds_read_b128 v[194:197], v152 offset:2048
	ds_read_b128 v[198:201], v152 offset:3072
	ds_read_b128 v[202:205], v152 offset:4096
	ds_read_b128 v[206:209], v152 offset:5120
	ds_read_b128 v[210:213], v152 offset:6144
	ds_read_b128 v[214:217], v152 offset:7168
	global_load_lds_dwordx4 v[146:147], off
	v_lshl_add_u64 v[146:147], s[72:73], 0, v[140:141]
	s_add_i32 m0, s71, 0xe000
	s_nop 0
	global_load_lds_dwordx4 v[146:147], off
	s_cmp_eq_u32 s100, 1
	s_cbranch_scc1 .Lrwp3b_a8
	s_waitcnt vmcnt(8)
	s_branch .Lrwp3b_adone
.Lrwp3b_a8:
	s_waitcnt vmcnt(16)
.Lrwp3b_adone:
	s_waitcnt lgkmcnt(0)
	s_barrier
	s_setprio 1
	s_waitcnt lgkmcnt(0)
	v_mfma_f32_16x16x32_bf16 v[126:129], v[154:157], v[186:189], v[126:129]
	v_mfma_f32_16x16x32_bf16 v[122:125], v[162:165], v[186:189], v[122:125]
	v_mfma_f32_16x16x32_bf16 v[110:113], v[154:157], v[194:197], v[110:113]
	v_mfma_f32_16x16x32_bf16 v[106:109], v[162:165], v[194:197], v[106:109]
	v_mfma_f32_16x16x32_bf16 v[94:97], v[154:157], v[202:205], v[94:97]
	v_mfma_f32_16x16x32_bf16 v[90:93], v[162:165], v[202:205], v[90:93]
	v_mfma_f32_16x16x32_bf16 v[78:81], v[154:157], v[210:213], v[78:81]
	v_mfma_f32_16x16x32_bf16 v[74:77], v[162:165], v[210:213], v[74:77]
	v_mfma_f32_16x16x32_bf16 v[126:129], v[158:161], v[190:193], v[126:129]
	v_mfma_f32_16x16x32_bf16 v[122:125], v[166:169], v[190:193], v[122:125]
	v_mfma_f32_16x16x32_bf16 v[110:113], v[158:161], v[198:201], v[110:113]
	v_mfma_f32_16x16x32_bf16 v[106:109], v[166:169], v[198:201], v[106:109]
	v_mfma_f32_16x16x32_bf16 v[94:97], v[158:161], v[206:209], v[94:97]
	v_mfma_f32_16x16x32_bf16 v[90:93], v[166:169], v[206:209], v[90:93]
	v_mfma_f32_16x16x32_bf16 v[78:81], v[158:161], v[214:217], v[78:81]
	v_mfma_f32_16x16x32_bf16 v[74:77], v[166:169], v[214:217], v[74:77]
	s_setprio 0
	s_setprio 1
	v_mfma_f32_16x16x32_bf16 v[118:121], v[170:173], v[186:189], v[118:121]
	v_mfma_f32_16x16x32_bf16 v[114:117], v[178:181], v[186:189], v[114:117]
	v_mfma_f32_16x16x32_bf16 v[102:105], v[170:173], v[194:197], v[102:105]
	v_mfma_f32_16x16x32_bf16 v[98:101], v[178:181], v[194:197], v[98:101]
	v_mfma_f32_16x16x32_bf16 v[86:89], v[170:173], v[202:205], v[86:89]
	v_mfma_f32_16x16x32_bf16 v[82:85], v[178:181], v[202:205], v[82:85]
	v_mfma_f32_16x16x32_bf16 v[70:73], v[170:173], v[210:213], v[70:73]
	v_mfma_f32_16x16x32_bf16 v[66:69], v[178:181], v[210:213], v[66:69]
	v_mfma_f32_16x16x32_bf16 v[118:121], v[174:177], v[190:193], v[118:121]
	v_mfma_f32_16x16x32_bf16 v[114:117], v[182:185], v[190:193], v[114:117]
	v_mfma_f32_16x16x32_bf16 v[102:105], v[174:177], v[198:201], v[102:105]
	v_mfma_f32_16x16x32_bf16 v[98:101], v[182:185], v[198:201], v[98:101]
	v_mfma_f32_16x16x32_bf16 v[86:89], v[174:177], v[206:209], v[86:89]
	v_mfma_f32_16x16x32_bf16 v[82:85], v[182:185], v[206:209], v[82:85]
	v_mfma_f32_16x16x32_bf16 v[70:73], v[174:177], v[214:217], v[70:73]
	v_mfma_f32_16x16x32_bf16 v[66:69], v[182:185], v[214:217], v[66:69]
	s_setprio 0
	s_barrier
	s_add_i32 s6, s87, s31
	v_lshl_add_u64 v[146:147], s[74:75], 0, v[132:133]
	s_mov_b32 m0, s6
	ds_read_b128 v[186:189], v152 offset:16384
	ds_read_b128 v[190:193], v152 offset:17408
	ds_read_b128 v[194:197], v152 offset:18432
	ds_read_b128 v[198:201], v152 offset:19456
	ds_read_b128 v[202:205], v152 offset:20480
	ds_read_b128 v[206:209], v152 offset:21504
	ds_read_b128 v[210:213], v152 offset:22528
	ds_read_b128 v[214:217], v152 offset:23552
	global_load_lds_dwordx4 v[146:147], off
	s_add_i32 m0, s6, 0x2000
	s_add_u32 s6, s74, 0x20000
	v_lshl_add_u64 v[218:219], s[74:75], 0, v[136:137]
	s_addc_u32 s7, s75, 0
	s_add_i32 s95, s88, s31
	global_load_lds_dwordx4 v[218:219], off
	v_lshl_add_u64 v[220:221], s[6:7], 0, v[132:133]
	s_mov_b32 m0, s95
	v_lshl_add_u64 v[222:223], s[76:77], 0, v[134:135]
	global_load_lds_dwordx4 v[220:221], off
	v_lshl_add_u64 v[220:221], s[6:7], 0, v[136:137]
	s_add_i32 m0, s95, 0x2000
	s_nop 0
	global_load_lds_dwordx4 v[220:221], off
	v_lshl_add_u64 v[220:221], s[76:77], 0, v[130:131]
	s_mov_b32 m0, s71
	s_nop 0
	global_load_lds_dwordx4 v[220:221], off
	s_mov_b32 m0, s78
	s_nop 0
	global_load_lds_dwordx4 v[222:223], off
	s_cmp_eq_u32 s100, 1
	s_cbranch_scc1 .Lrwp3b_b8
	s_waitcnt vmcnt(8)
	s_branch .Lrwp3b_bdone

.Lrwp3b_bdone:
	s_mov_b32 s100, 0
	s_waitcnt lgkmcnt(0)
	s_barrier
	s_setprio 1
	s_waitcnt lgkmcnt(0)
	v_mfma_f32_16x16x32_bf16 v[62:65], v[154:157], v[186:189], v[62:65]
	v_mfma_f32_16x16x32_bf16 v[58:61], v[162:165], v[186:189], v[58:61]
	v_mfma_f32_16x16x32_bf16 v[46:49], v[154:157], v[194:197], v[46:49]
	v_mfma_f32_16x16x32_bf16 v[42:45], v[162:165], v[194:197], v[42:45]
	v_mfma_f32_16x16x32_bf16 v[30:33], v[154:157], v[202:205], v[30:33]
	v_mfma_f32_16x16x32_bf16 v[26:29], v[162:165], v[202:205], v[26:29]
	v_mfma_f32_16x16x32_bf16 v[14:17], v[154:157], v[210:213], v[14:17]
	v_mfma_f32_16x16x32_bf16 v[10:13], v[162:165], v[210:213], v[10:13]
	v_mfma_f32_16x16x32_bf16 v[62:65], v[158:161], v[190:193], v[62:65]
	v_mfma_f32_16x16x32_bf16 v[58:61], v[166:169], v[190:193], v[58:61]
	v_mfma_f32_16x16x32_bf16 v[46:49], v[158:161], v[198:201], v[46:49]
	v_mfma_f32_16x16x32_bf16 v[42:45], v[166:169], v[198:201], v[42:45]
	v_mfma_f32_16x16x32_bf16 v[30:33], v[158:161], v[206:209], v[30:33]
	v_mfma_f32_16x16x32_bf16 v[26:29], v[166:169], v[206:209], v[26:29]
	v_mfma_f32_16x16x32_bf16 v[14:17], v[158:161], v[214:217], v[14:17]
	v_mfma_f32_16x16x32_bf16 v[10:13], v[166:169], v[214:217], v[10:13]
	s_setprio 0
	s_setprio 1
	v_mfma_f32_16x16x32_bf16 v[54:57], v[170:173], v[186:189], v[54:57]
	v_mfma_f32_16x16x32_bf16 v[50:53], v[178:181], v[186:189], v[50:53]
	v_mfma_f32_16x16x32_bf16 v[38:41], v[170:173], v[194:197], v[38:41]
	v_mfma_f32_16x16x32_bf16 v[34:37], v[178:181], v[194:197], v[34:37]
	v_mfma_f32_16x16x32_bf16 v[22:25], v[170:173], v[202:205], v[22:25]
	v_mfma_f32_16x16x32_bf16 v[18:21], v[178:181], v[202:205], v[18:21]
	v_mfma_f32_16x16x32_bf16 v[6:9], v[170:173], v[210:213], v[6:9]
	v_mfma_f32_16x16x32_bf16 v[2:5], v[178:181], v[210:213], v[2:5]
	v_mfma_f32_16x16x32_bf16 v[54:57], v[174:177], v[190:193], v[54:57]
	v_mfma_f32_16x16x32_bf16 v[50:53], v[182:185], v[190:193], v[50:53]
	v_mfma_f32_16x16x32_bf16 v[38:41], v[174:177], v[198:201], v[38:41]
	v_mfma_f32_16x16x32_bf16 v[34:37], v[182:185], v[198:201], v[34:37]
	v_mfma_f32_16x16x32_bf16 v[22:25], v[174:177], v[206:209], v[22:25]
	v_mfma_f32_16x16x32_bf16 v[18:21], v[182:185], v[206:209], v[18:21]
	v_mfma_f32_16x16x32_bf16 v[6:9], v[174:177], v[214:217], v[6:9]
	v_mfma_f32_16x16x32_bf16 v[2:5], v[182:185], v[214:217], v[2:5]
	s_setprio 0
	s_barrier
	s_add_i32 s95, 0, 0x18000
	v_add_u32_e32 v153, s95, v149
	s_add_i32 s96, 0, 0x1c000
	ds_read_b128 v[154:157], v153
	ds_read_b128 v[158:161], v153 offset:1024
	ds_read_b128 v[162:165], v153 offset:2048
	ds_read_b128 v[166:169], v153 offset:3072
	v_add_u32_e32 v153, s96, v149
	ds_read_b128 v[170:173], v153
	ds_read_b128 v[174:177], v153 offset:1024
	ds_read_b128 v[178:181], v153 offset:2048
	ds_read_b128 v[182:185], v153 offset:3072
	s_add_u32 s6, s76, 0x20000
	s_addc_u32 s7, s77, 0
	s_mov_b32 m0, s79
	v_lshl_add_u64 v[224:225], s[6:7], 0, v[130:131]
	ds_read_b128 v[186:189], v152 offset:32768
	ds_read_b128 v[190:193], v152 offset:33792
	ds_read_b128 v[194:197], v152 offset:34816
	ds_read_b128 v[198:201], v152 offset:35840
	ds_read_b128 v[202:205], v152 offset:36864
	ds_read_b128 v[206:209], v152 offset:37888
	ds_read_b128 v[210:213], v152 offset:38912
	ds_read_b128 v[214:217], v152 offset:39936
	global_load_lds_dwordx4 v[224:225], off
	v_lshl_add_u64 v[224:225], s[6:7], 0, v[134:135]
	s_mov_b32 m0, s80
	s_nop 0
	global_load_lds_dwordx4 v[224:225], off
	s_waitcnt vmcnt(8)
	s_waitcnt lgkmcnt(0)
	s_barrier
	s_setprio 1
	s_waitcnt lgkmcnt(0)
	v_mfma_f32_16x16x32_bf16 v[126:129], v[154:157], v[186:189], v[126:129]
	v_mfma_f32_16x16x32_bf16 v[122:125], v[162:165], v[186:189], v[122:125]
	v_mfma_f32_16x16x32_bf16 v[110:113], v[154:157], v[194:197], v[110:113]
	v_mfma_f32_16x16x32_bf16 v[106:109], v[162:165], v[194:197], v[106:109]
	v_mfma_f32_16x16x32_bf16 v[94:97], v[154:157], v[202:205], v[94:97]
	v_mfma_f32_16x16x32_bf16 v[90:93], v[162:165], v[202:205], v[90:93]
	v_mfma_f32_16x16x32_bf16 v[78:81], v[154:157], v[210:213], v[78:81]
	v_mfma_f32_16x16x32_bf16 v[74:77], v[162:165], v[210:213], v[74:77]
	v_mfma_f32_16x16x32_bf16 v[126:129], v[158:161], v[190:193], v[126:129]
	v_mfma_f32_16x16x32_bf16 v[122:125], v[166:169], v[190:193], v[122:125]
	v_mfma_f32_16x16x32_bf16 v[110:113], v[158:161], v[198:201], v[110:113]
	v_mfma_f32_16x16x32_bf16 v[106:109], v[166:169], v[198:201], v[106:109]
	v_mfma_f32_16x16x32_bf16 v[94:97], v[158:161], v[206:209], v[94:97]
	v_mfma_f32_16x16x32_bf16 v[90:93], v[166:169], v[206:209], v[90:93]
	v_mfma_f32_16x16x32_bf16 v[78:81], v[158:161], v[214:217], v[78:81]
	v_mfma_f32_16x16x32_bf16 v[74:77], v[166:169], v[214:217], v[74:77]
	s_setprio 0
	s_setprio 1
	v_mfma_f32_16x16x32_bf16 v[118:121], v[170:173], v[186:189], v[118:121]
	v_mfma_f32_16x16x32_bf16 v[114:117], v[178:181], v[186:189], v[114:117]
	v_mfma_f32_16x16x32_bf16 v[102:105], v[170:173], v[194:197], v[102:105]
	v_mfma_f32_16x16x32_bf16 v[98:101], v[178:181], v[194:197], v[98:101]
	v_mfma_f32_16x16x32_bf16 v[86:89], v[170:173], v[202:205], v[86:89]
	v_mfma_f32_16x16x32_bf16 v[82:85], v[178:181], v[202:205], v[82:85]
	v_mfma_f32_16x16x32_bf16 v[70:73], v[170:173], v[210:213], v[70:73]
	v_mfma_f32_16x16x32_bf16 v[66:69], v[178:181], v[210:213], v[66:69]
	v_mfma_f32_16x16x32_bf16 v[118:121], v[174:177], v[190:193], v[118:121]
	v_mfma_f32_16x16x32_bf16 v[114:117], v[182:185], v[190:193], v[114:117]
	v_mfma_f32_16x16x32_bf16 v[102:105], v[174:177], v[198:201], v[102:105]
	v_mfma_f32_16x16x32_bf16 v[98:101], v[182:185], v[198:201], v[98:101]
	v_mfma_f32_16x16x32_bf16 v[86:89], v[174:177], v[206:209], v[86:89]
	v_mfma_f32_16x16x32_bf16 v[82:85], v[182:185], v[206:209], v[82:85]
	v_mfma_f32_16x16x32_bf16 v[70:73], v[174:177], v[214:217], v[70:73]
	v_mfma_f32_16x16x32_bf16 v[66:69], v[182:185], v[214:217], v[66:69]
	s_setprio 0
	s_barrier
	s_add_i32 s6, s95, s31
	v_lshl_add_u64 v[146:147], v[146:147], 0, s[20:21]
	s_mov_b32 m0, s6
	ds_read_b128 v[186:189], v152 offset:49152
	ds_read_b128 v[190:193], v152 offset:50176
	ds_read_b128 v[194:197], v152 offset:51200
	ds_read_b128 v[198:201], v152 offset:52224
	ds_read_b128 v[202:205], v152 offset:53248
	ds_read_b128 v[206:209], v152 offset:54272
	ds_read_b128 v[210:213], v152 offset:55296
	ds_read_b128 v[214:217], v152 offset:56320
	global_load_lds_dwordx4 v[146:147], off
	s_add_i32 m0, s6, 0x2000
	s_add_u32 s6, s74, 0x20080
	v_lshl_add_u64 v[146:147], v[218:219], 0, s[20:21]
	s_addc_u32 s7, s75, 0
	s_add_i32 s74, s96, s31
	global_load_lds_dwordx4 v[146:147], off
	v_lshl_add_u64 v[146:147], s[6:7], 0, v[132:133]
	s_mov_b32 m0, s74
	s_nop 0
	global_load_lds_dwordx4 v[146:147], off
	v_lshl_add_u64 v[146:147], s[6:7], 0, v[136:137]
	s_add_i32 m0, s74, 0x2000
	s_nop 0
	global_load_lds_dwordx4 v[146:147], off
	v_lshl_add_u64 v[146:147], v[220:221], 0, s[20:21]
	s_mov_b32 m0, s84
	s_nop 0
	global_load_lds_dwordx4 v[146:147], off
	v_lshl_add_u64 v[146:147], v[222:223], 0, s[20:21]
	s_mov_b32 m0, s85
	s_nop 0
	global_load_lds_dwordx4 v[146:147], off
	s_waitcnt vmcnt(8)
	s_waitcnt lgkmcnt(0)
	s_barrier
	s_setprio 1
	s_waitcnt lgkmcnt(0)
	v_mfma_f32_16x16x32_bf16 v[62:65], v[154:157], v[186:189], v[62:65]
	v_mfma_f32_16x16x32_bf16 v[58:61], v[162:165], v[186:189], v[58:61]
	v_mfma_f32_16x16x32_bf16 v[46:49], v[154:157], v[194:197], v[46:49]
	v_mfma_f32_16x16x32_bf16 v[42:45], v[162:165], v[194:197], v[42:45]
	v_mfma_f32_16x16x32_bf16 v[30:33], v[154:157], v[202:205], v[30:33]
	v_mfma_f32_16x16x32_bf16 v[26:29], v[162:165], v[202:205], v[26:29]
	v_mfma_f32_16x16x32_bf16 v[14:17], v[154:157], v[210:213], v[14:17]
	v_mfma_f32_16x16x32_bf16 v[10:13], v[162:165], v[210:213], v[10:13]
	v_mfma_f32_16x16x32_bf16 v[62:65], v[158:161], v[190:193], v[62:65]
	v_mfma_f32_16x16x32_bf16 v[58:61], v[166:169], v[190:193], v[58:61]
	v_mfma_f32_16x16x32_bf16 v[46:49], v[158:161], v[198:201], v[46:49]
	v_mfma_f32_16x16x32_bf16 v[42:45], v[166:169], v[198:201], v[42:45]
	v_mfma_f32_16x16x32_bf16 v[30:33], v[158:161], v[206:209], v[30:33]
	v_mfma_f32_16x16x32_bf16 v[26:29], v[166:169], v[206:209], v[26:29]
	v_mfma_f32_16x16x32_bf16 v[14:17], v[158:161], v[214:217], v[14:17]
	v_mfma_f32_16x16x32_bf16 v[10:13], v[166:169], v[214:217], v[10:13]
	s_setprio 0
	s_setprio 1
	v_mfma_f32_16x16x32_bf16 v[54:57], v[170:173], v[186:189], v[54:57]
	v_mfma_f32_16x16x32_bf16 v[50:53], v[178:181], v[186:189], v[50:53]
	v_mfma_f32_16x16x32_bf16 v[38:41], v[170:173], v[194:197], v[38:41]
	v_mfma_f32_16x16x32_bf16 v[34:37], v[178:181], v[194:197], v[34:37]
	v_mfma_f32_16x16x32_bf16 v[22:25], v[170:173], v[202:205], v[22:25]
	v_mfma_f32_16x16x32_bf16 v[18:21], v[178:181], v[202:205], v[18:21]
	v_mfma_f32_16x16x32_bf16 v[6:9], v[170:173], v[210:213], v[6:9]
	v_mfma_f32_16x16x32_bf16 v[2:5], v[178:181], v[210:213], v[2:5]
	v_mfma_f32_16x16x32_bf16 v[54:57], v[174:177], v[190:193], v[54:57]
	v_mfma_f32_16x16x32_bf16 v[50:53], v[182:185], v[190:193], v[50:53]
	v_mfma_f32_16x16x32_bf16 v[38:41], v[174:177], v[198:201], v[38:41]
	v_mfma_f32_16x16x32_bf16 v[34:37], v[182:185], v[198:201], v[34:37]
	v_mfma_f32_16x16x32_bf16 v[22:25], v[174:177], v[206:209], v[22:25]
	v_mfma_f32_16x16x32_bf16 v[18:21], v[182:185], v[206:209], v[18:21]
	v_mfma_f32_16x16x32_bf16 v[6:9], v[174:177], v[214:217], v[6:9]
	v_mfma_f32_16x16x32_bf16 v[2:5], v[182:185], v[214:217], v[2:5]
	s_setprio 0
	s_barrier
	s_add_i32 s94, s94, 2
	s_add_u32 s72, s72, 0x100
	s_addc_u32 s73, s73, 0
	s_add_u32 s92, s92, 0x100
	s_addc_u32 s93, s93, 0
	s_cmp_gt_u32 s94, 5
	s_cbranch_scc0 .LBB0_584
	s_branch .Lrwp3b_exit
.Lrwp3b_prelaxed:
	s_waitcnt vmcnt(8)
	s_branch .Lrwp3b_pdone
